# baseline (speedup 1.0000x reference)
; template <int EPI>
; __device__ __forceinline__ void gemm_phase(const Params& p, const u16* __restrict__ A, const u16* __restrict__ Bt, int K, int nN,
;                            u16* __restrict__ Cout, int ldc) {
;     ...
; #pragma unroll
;       for (int half = 0; half < 2; ++half) {
; #pragma unroll
;         for (int mm = 0; mm < 4; ++mm) {
;           const int m = half * 4 + mm;
; #pragma unroll
;           for (int j = 0; j < 4; ++j) {
;             float rs = 1.f;
;             if (EPI == EPI_WIN) rs = rsl[wr * 128 + m * 16 + fqe * 4 + j];
;             u16* d = stg + (wr * 64 + mm * 16 + fqe * 4 + j) * 256 + (fre & 7);
; #pragma unroll
;             for (int n = 0; n < 4; ++n) {
;               const int chunk = (wc * 8 + n * 2 + (fre >> 3)) ^ (fqe << 1);
;               d[chunk * 8] = f2bf(acc[m][n][j] * rs);
;             }
;           }
;           __builtin_amdgcn_sched_barrier(0);
;         }
.LBB0_854:
	v_mov_b32_e32 v136, v192
	v_mov_b32_e32 v137, v173
	v_mov_b32_e32 v128, v174
	s_nop 0
	v_lshlrev_b32_e32 v138, 4, v136
	v_add_u32_e32 v131, v196, v138
	ds_read_b128 v[132:135], v131
	v_and_b32_e32 v139, 7, v128
	v_add_u32_e32 v140, v128, v197
	v_lshlrev_b32_e32 v136, 11, v136
	v_lshlrev_b32_e32 v139, 1, v139
	s_waitcnt lgkmcnt(0)
	v_mul_f32_e32 v124, v124, v132
	v_add3_u32 v136, v205, v139, v136
	v_cvt_pk_bf16_f32 v139, v124, s0
	v_bitop3_b32 v124, v140, v138, -8 bitop3:0x6c
	v_and_b32_e32 v143, -8, v140
	v_lshl_add_u32 v124, v124, 1, v136
	v_mul_f32_e32 v120, v120, v132
	ds_write_b16 v124, v139
	v_cvt_pk_bf16_f32 v139, v120, s0
	v_add_u32_e32 v120, 16, v143
	v_xor_b32_e32 v120, v120, v138
	v_lshl_add_u32 v120, v120, 1, v136
	v_mul_f32_e32 v116, v116, v132
	v_mul_f32_e32 v112, v112, v132
	ds_write_b16 v120, v139
	v_cvt_pk_bf16_f32 v139, v116, s0
	v_add_u32_e32 v116, 32, v143
	v_cvt_pk_bf16_f32 v132, v112, s0
	v_add_u32_e32 v112, 48, v143
	v_xor_b32_e32 v116, v116, v138
	v_xor_b32_e32 v112, v112, v138
	v_mul_f32_e32 v113, v113, v133
	v_lshl_add_u32 v116, v116, 1, v136
	v_lshl_add_u32 v112, v112, 1, v136
	v_cvt_pk_bf16_f32 v113, v113, s0
	ds_write_b16 v116, v139
	v_mul_f32_e32 v121, v121, v133
	v_mul_f32_e32 v117, v117, v133
	ds_write_b16 v112, v113 offset:512
	v_mul_f32_e32 v113, v126, v134
	v_cvt_pk_bf16_f32 v121, v121, s0
	v_cvt_pk_bf16_f32 v117, v117, s0
	v_cvt_pk_bf16_f32 v113, v113, s0
	ds_write_b16 v112, v132
	v_mul_f32_e32 v125, v125, v133
	ds_write_b16 v120, v121 offset:512
	ds_write_b16 v116, v117 offset:512
	ds_write_b16 v124, v113 offset:1024
	v_mul_f32_e32 v113, v122, v134
	v_cvt_pk_bf16_f32 v125, v125, s0
	v_cvt_pk_bf16_f32 v113, v113, s0
	ds_write_b16 v124, v125 offset:512
	ds_write_b16 v120, v113 offset:1024
	v_mul_f32_e32 v113, v118, v134
	v_cvt_pk_bf16_f32 v113, v113, s0
	ds_write_b16 v116, v113 offset:1024
	v_mul_f32_e32 v113, v114, v134
	v_cvt_pk_bf16_f32 v113, v113, s0
	ds_write_b16 v112, v113 offset:1024
	v_mul_f32_e32 v113, v127, v135
	v_cvt_pk_bf16_f32 v113, v113, s0
	ds_write_b16 v124, v113 offset:1536
	v_mul_f32_e32 v113, v123, v135
	v_cvt_pk_bf16_f32 v113, v113, s0
	ds_write_b16 v120, v113 offset:1536
	v_mul_f32_e32 v113, v119, v135
	v_and_b32_e32 v128, 31, v137
	v_lshrrev_b32_e32 v129, 6, v137
	v_cvt_pk_bf16_f32 v113, v113, s0
	v_bitop3_b32 v129, v129, v128, 6 bitop3:0x6c
	ds_write_b16 v116, v113 offset:1536
	v_mul_f32_e32 v113, v115, v135
	v_lshl_or_b32 v141, v129, 4, v188
	v_lshl_or_b32 v128, v128, 3, s18
	v_mov_b32_e32 v129, v172
	v_ashrrev_i32_e32 v142, 5, v137
	v_cvt_pk_bf16_f32 v113, v113, s0
	v_lshl_add_u64 v[128:129], v[128:129], 1, s[10:11]
	v_lshl_add_u32 v130, v142, 9, v141
	ds_write_b16 v112, v113 offset:1536
	ds_read_b128 v[132:135], v131 offset:64
	s_waitcnt lgkmcnt(0)
	v_mul_f32_e32 v108, v108, v132
	v_mul_f32_e32 v96, v96, v132
	v_mul_f32_e32 v104, v104, v132
	v_cvt_pk_bf16_f32 v108, v108, s0
	v_cvt_pk_bf16_f32 v96, v96, s0
	v_mul_f32_e32 v100, v100, v132
	v_cvt_pk_bf16_f32 v104, v104, s0
	ds_write_b16 v124, v108 offset:8192
	ds_write_b16 v120, v104 offset:8192
	ds_write_b16 v112, v96 offset:8192
	v_mul_f32_e32 v96, v109, v133
	v_cvt_pk_bf16_f32 v100, v100, s0
	v_cvt_pk_bf16_f32 v96, v96, s0
	ds_write_b16 v116, v100 offset:8192
	ds_write_b16 v124, v96 offset:8704
	v_mul_f32_e32 v96, v105, v133
	v_cvt_pk_bf16_f32 v96, v96, s0
	ds_write_b16 v120, v96 offset:8704
	v_mul_f32_e32 v96, v101, v133
	v_cvt_pk_bf16_f32 v96, v96, s0
	ds_write_b16 v116, v96 offset:8704
	v_mul_f32_e32 v96, v97, v133
	v_cvt_pk_bf16_f32 v96, v96, s0
	ds_write_b16 v112, v96 offset:8704
	v_mul_f32_e32 v96, v110, v134
	v_cvt_pk_bf16_f32 v96, v96, s0
	ds_write_b16 v124, v96 offset:9216
	v_mul_f32_e32 v96, v106, v134
	v_cvt_pk_bf16_f32 v96, v96, s0
	ds_write_b16 v120, v96 offset:9216
	v_mul_f32_e32 v96, v102, v134
	v_cvt_pk_bf16_f32 v96, v96, s0
	ds_write_b16 v116, v96 offset:9216
	v_mul_f32_e32 v96, v98, v134
	v_cvt_pk_bf16_f32 v96, v96, s0
	ds_write_b16 v112, v96 offset:9216
	v_mul_f32_e32 v96, v111, v135
	v_cvt_pk_bf16_f32 v96, v96, s0
	ds_write_b16 v124, v96 offset:9728
	v_mul_f32_e32 v96, v107, v135
	v_cvt_pk_bf16_f32 v96, v96, s0
	ds_write_b16 v120, v96 offset:9728
	v_mul_f32_e32 v96, v103, v135
	v_cvt_pk_bf16_f32 v96, v96, s0
	ds_write_b16 v116, v96 offset:9728
	v_mul_f32_e32 v96, v99, v135
	v_cvt_pk_bf16_f32 v96, v96, s0
	ds_write_b16 v112, v96 offset:9728
	ds_read_b128 v[96:99], v131 offset:128
	s_waitcnt lgkmcnt(0)
	v_mul_f32_e32 v92, v92, v96
	v_mul_f32_e32 v80, v80, v96
	v_mul_f32_e32 v88, v88, v96
	v_cvt_pk_bf16_f32 v92, v92, s0
	v_cvt_pk_bf16_f32 v80, v80, s0
	v_mul_f32_e32 v84, v84, v96
	v_cvt_pk_bf16_f32 v88, v88, s0
	ds_write_b16 v124, v92 offset:16384
	ds_write_b16 v120, v88 offset:16384
	ds_write_b16 v112, v80 offset:16384
	v_mul_f32_e32 v80, v93, v97
	v_cvt_pk_bf16_f32 v84, v84, s0
	v_cvt_pk_bf16_f32 v80, v80, s0
	ds_write_b16 v116, v84 offset:16384
	ds_write_b16 v124, v80 offset:16896
	v_mul_f32_e32 v80, v89, v97
	v_cvt_pk_bf16_f32 v80, v80, s0
	ds_write_b16 v120, v80 offset:16896
	v_mul_f32_e32 v80, v85, v97
	v_cvt_pk_bf16_f32 v80, v80, s0
	ds_write_b16 v116, v80 offset:16896
	v_mul_f32_e32 v80, v81, v97
	v_cvt_pk_bf16_f32 v80, v80, s0
	ds_write_b16 v112, v80 offset:16896
	v_mul_f32_e32 v80, v94, v98
	v_cvt_pk_bf16_f32 v80, v80, s0
	ds_write_b16 v124, v80 offset:17408
	v_mul_f32_e32 v80, v90, v98
	v_cvt_pk_bf16_f32 v80, v80, s0
	ds_write_b16 v120, v80 offset:17408
	v_mul_f32_e32 v80, v86, v98
	v_cvt_pk_bf16_f32 v80, v80, s0
	ds_write_b16 v116, v80 offset:17408
	v_mul_f32_e32 v80, v82, v98
	v_cvt_pk_bf16_f32 v80, v80, s0
	ds_write_b16 v112, v80 offset:17408
	v_mul_f32_e32 v80, v95, v99
	v_cvt_pk_bf16_f32 v80, v80, s0
	ds_write_b16 v124, v80 offset:17920
	v_mul_f32_e32 v80, v91, v99
	v_cvt_pk_bf16_f32 v80, v80, s0
	ds_write_b16 v120, v80 offset:17920
	v_mul_f32_e32 v80, v87, v99
	v_cvt_pk_bf16_f32 v80, v80, s0
	ds_write_b16 v116, v80 offset:17920
	v_mul_f32_e32 v80, v83, v99
	v_cvt_pk_bf16_f32 v80, v80, s0
	ds_write_b16 v112, v80 offset:17920
	ds_read_b128 v[80:83], v131 offset:192
	s_waitcnt lgkmcnt(0)
; template <int EPI>
; __device__ __forceinline__ void gemm_phase(const Params& p, const u16* __restrict__ A, const u16* __restrict__ Bt, int K, int nN,
;                            u16* __restrict__ Cout, int ldc) {
;     ...
; #pragma unroll
;       for (int half = 0; half < 2; ++half) {
; #pragma unroll
;         for (int mm = 0; mm < 4; ++mm) {
;           const int m = half * 4 + mm;
; #pragma unroll
;           for (int j = 0; j < 4; ++j) {
;             float rs = 1.f;
;             if (EPI == EPI_WIN) rs = rsl[wr * 128 + m * 16 + fqe * 4 + j];
;             u16* d = stg + (wr * 64 + mm * 16 + fqe * 4 + j) * 256 + (fre & 7);
; #pragma unroll
;             for (int n = 0; n < 4; ++n) {
;               const int chunk = (wc * 8 + n * 2 + (fre >> 3)) ^ (fqe << 1);
;               d[chunk * 8] = f2bf(acc[m][n][j] * rs);
;             }
;           }
;           __builtin_amdgcn_sched_barrier(0);
;         }
;         __syncthreads();
; #pragma unroll
;         for (int it = 0; it < 8; ++it) {
;           const int id = it * 512 + tide, r = id >> 5, ck = id & 31;
;           const uint4 v = *(const uint4*)(stg + r * 256 + ((ck ^ (((r >> 2) & 3) << 1)) * 8));
;           const int grow = brow + (r >> 6) * 128 + half * 64 + (r & 63);
;           if (EPI == EPI_WIN) { typedef __attribute__((ext_vector_type(4))) unsigned u32x4_; const u32x4_ t_ = {v.x, v.y, v.z, v.w};
;             __builtin_nontemporal_store(t_, (u32x4_*)(Cout + (unsigned)grow * (unsigned)ldc + (unsigned)(bcol + ck * 8))); }
;           else *(uint4*)(Cout + (unsigned)grow * (unsigned)ldc + (unsigned)(bcol + ck * 8)) = v;
;         }
;         asm volatile("s_waitcnt lgkmcnt(0)" ::: "memory"); __builtin_amdgcn_s_barrier();
	v_mul_f32_e32 v76, v76, v80
	v_mul_f32_e32 v64, v64, v80
	v_mul_f32_e32 v72, v72, v80
	v_cvt_pk_bf16_f32 v76, v76, s0
	v_cvt_pk_bf16_f32 v64, v64, s0
	v_mul_f32_e32 v68, v68, v80
	v_cvt_pk_bf16_f32 v72, v72, s0
	ds_write_b16 v124, v76 offset:24576
	ds_write_b16 v120, v72 offset:24576
	ds_write_b16 v112, v64 offset:24576
	v_mul_f32_e32 v64, v77, v81
	v_cvt_pk_bf16_f32 v68, v68, s0
	v_cvt_pk_bf16_f32 v64, v64, s0
	ds_write_b16 v116, v68 offset:24576
	ds_write_b16 v124, v64 offset:25088
	v_mul_f32_e32 v64, v73, v81
	v_cvt_pk_bf16_f32 v64, v64, s0
	ds_write_b16 v120, v64 offset:25088
	v_mul_f32_e32 v64, v69, v81
	v_cvt_pk_bf16_f32 v64, v64, s0
	ds_write_b16 v116, v64 offset:25088
	v_mul_f32_e32 v64, v65, v81
	v_cvt_pk_bf16_f32 v64, v64, s0
	ds_write_b16 v112, v64 offset:25088
	v_mul_f32_e32 v64, v78, v82
	v_cvt_pk_bf16_f32 v64, v64, s0
	ds_write_b16 v124, v64 offset:25600
	v_mul_f32_e32 v64, v74, v82
	v_cvt_pk_bf16_f32 v64, v64, s0
	ds_write_b16 v120, v64 offset:25600
	v_mul_f32_e32 v64, v70, v82
	v_cvt_pk_bf16_f32 v64, v64, s0
	ds_write_b16 v116, v64 offset:25600
	v_mul_f32_e32 v64, v66, v82
	v_cvt_pk_bf16_f32 v64, v64, s0
	ds_write_b16 v112, v64 offset:25600
	v_mul_f32_e32 v64, v79, v83
	v_cvt_pk_bf16_f32 v64, v64, s0
	ds_write_b16 v124, v64 offset:26112
	v_mul_f32_e32 v64, v75, v83
	v_cvt_pk_bf16_f32 v64, v64, s0
	ds_write_b16 v120, v64 offset:26112
	v_mul_f32_e32 v64, v71, v83
	v_cvt_pk_bf16_f32 v64, v64, s0
	ds_write_b16 v116, v64 offset:26112
	v_mul_f32_e32 v64, v67, v83
	v_cvt_pk_bf16_f32 v64, v64, s0
	ds_write_b16 v112, v64 offset:26112
	v_ashrrev_i32_e32 v68, 4, v137
	s_waitcnt lgkmcnt(0)
	s_barrier
	ds_read_b128 v[64:67], v130
	v_and_b32_e32 v70, 0xffffff80, v68
	v_add_u32_e32 v68, s16, v70
	v_and_b32_e32 v71, 63, v142
	v_or_b32_e32 v68, v68, v71
	v_mul_lo_u32 v68, v68, s58
	v_mov_b32_e32 v69, v172
	v_lshl_add_u64 v[68:69], v[68:69], 1, v[128:129]
	s_waitcnt lgkmcnt(0)
	global_store_dwordx4 v[68:69], v[64:67], off sc0 sc1 nt
	v_add_u32_e32 v68, 0x200, v137
	v_ashrrev_i32_e32 v69, 5, v68
	v_lshl_add_u32 v72, v69, 9, v141
	v_ashrrev_i32_e32 v68, 4, v68
	ds_read_b128 v[64:67], v72
	v_and_b32_e32 v73, 0xffffff80, v68
	v_add_u32_e32 v68, s16, v73
	v_and_b32_e32 v74, 63, v69
	v_or_b32_e32 v68, v68, v74
	v_mul_lo_u32 v68, v68, s58
	v_mov_b32_e32 v69, v172
	v_lshl_add_u64 v[68:69], v[68:69], 1, v[128:129]
	s_waitcnt lgkmcnt(0)
	global_store_dwordx4 v[68:69], v[64:67], off sc0 sc1 nt
	v_add_u32_e32 v68, 0x400, v137
	v_ashrrev_i32_e32 v69, 5, v68
	v_lshl_add_u32 v75, v69, 9, v141
	v_ashrrev_i32_e32 v68, 4, v68
	ds_read_b128 v[64:67], v75
	v_and_b32_e32 v76, 0xffffff80, v68
	v_add_u32_e32 v68, s16, v76
	v_and_b32_e32 v77, 63, v69
	v_or_b32_e32 v68, v68, v77
	v_mul_lo_u32 v68, v68, s58
	v_mov_b32_e32 v69, v172
	v_lshl_add_u64 v[68:69], v[68:69], 1, v[128:129]
	s_waitcnt lgkmcnt(0)
	global_store_dwordx4 v[68:69], v[64:67], off sc0 sc1 nt
	v_add_u32_e32 v68, 0x600, v137
	v_ashrrev_i32_e32 v69, 5, v68
	v_lshl_add_u32 v78, v69, 9, v141
	v_ashrrev_i32_e32 v68, 4, v68
	ds_read_b128 v[64:67], v78
	v_and_b32_e32 v79, 0xffffff80, v68
	v_add_u32_e32 v68, s16, v79
	v_and_b32_e32 v80, 63, v69
	v_or_b32_e32 v68, v68, v80
	v_mul_lo_u32 v68, v68, s58
	v_mov_b32_e32 v69, v172
	v_lshl_add_u64 v[68:69], v[68:69], 1, v[128:129]
	s_waitcnt lgkmcnt(0)
	global_store_dwordx4 v[68:69], v[64:67], off sc0 sc1 nt
	v_add_u32_e32 v68, 0x800, v137
	v_ashrrev_i32_e32 v69, 5, v68
	v_lshl_add_u32 v81, v69, 9, v141
	v_ashrrev_i32_e32 v68, 4, v68
	ds_read_b128 v[64:67], v81
	v_and_b32_e32 v82, 0xffffff80, v68
	v_add_u32_e32 v68, s16, v82
	v_and_b32_e32 v83, 63, v69
	v_or_b32_e32 v68, v68, v83
	v_mul_lo_u32 v68, v68, s58
	v_mov_b32_e32 v69, v172
	v_lshl_add_u64 v[68:69], v[68:69], 1, v[128:129]
	s_waitcnt lgkmcnt(0)
	global_store_dwordx4 v[68:69], v[64:67], off sc0 sc1 nt
	v_add_u32_e32 v68, 0xa00, v137
	v_ashrrev_i32_e32 v69, 5, v68
	v_lshl_add_u32 v84, v69, 9, v141
	v_ashrrev_i32_e32 v68, 4, v68
	ds_read_b128 v[64:67], v84
	v_and_b32_e32 v85, 0xffffff80, v68
	v_add_u32_e32 v68, s16, v85
	v_and_b32_e32 v86, 63, v69
	v_or_b32_e32 v68, v68, v86
	v_mul_lo_u32 v68, v68, s58
	v_mov_b32_e32 v69, v172
	v_lshl_add_u64 v[68:69], v[68:69], 1, v[128:129]
	s_waitcnt lgkmcnt(0)
	global_store_dwordx4 v[68:69], v[64:67], off sc0 sc1 nt
	v_add_u32_e32 v68, 0xc00, v137
	v_ashrrev_i32_e32 v69, 5, v68
	v_lshl_add_u32 v87, v69, 9, v141
	v_ashrrev_i32_e32 v68, 4, v68
	ds_read_b128 v[64:67], v87
	v_and_b32_e32 v88, 0xffffff80, v68
	v_add_u32_e32 v68, s16, v88
	v_and_b32_e32 v89, 63, v69
	v_or_b32_e32 v68, v68, v89
	v_mul_lo_u32 v68, v68, s58
	v_mov_b32_e32 v69, v172
	v_lshl_add_u64 v[68:69], v[68:69], 1, v[128:129]
	s_waitcnt lgkmcnt(0)
	global_store_dwordx4 v[68:69], v[64:67], off sc0 sc1 nt
	v_add_u32_e32 v68, 0xe00, v137
	v_ashrrev_i32_e32 v69, 5, v68
	v_lshl_add_u32 v90, v69, 9, v141
	v_ashrrev_i32_e32 v68, 4, v68
	ds_read_b128 v[64:67], v90
	v_and_b32_e32 v91, 0xffffff80, v68
	v_add_u32_e32 v68, s16, v91
	v_and_b32_e32 v92, 63, v69
	v_or_b32_e32 v68, v68, v92
	v_mul_lo_u32 v68, v68, s58
	v_mov_b32_e32 v69, v172
	v_lshl_add_u64 v[68:69], v[68:69], 1, v[128:129]
	s_waitcnt lgkmcnt(0)
	global_store_dwordx4 v[68:69], v[64:67], off sc0 sc1 nt
	s_waitcnt lgkmcnt(0)
	s_barrier
; template <int EPI>
; __device__ __forceinline__ void gemm_phase(const Params& p, const u16* __restrict__ A, const u16* __restrict__ Bt, int K, int nN,
;                            u16* __restrict__ Cout, int ldc) {
;     ...
; #pragma unroll
;       for (int half = 0; half < 2; ++half) {
; #pragma unroll
;         for (int mm = 0; mm < 4; ++mm) {
;           const int m = half * 4 + mm;
; #pragma unroll
;           for (int j = 0; j < 4; ++j) {
;             float rs = 1.f;
;             if (EPI == EPI_WIN) rs = rsl[wr * 128 + m * 16 + fqe * 4 + j];
;             u16* d = stg + (wr * 64 + mm * 16 + fqe * 4 + j) * 256 + (fre & 7);
; #pragma unroll
;             for (int n = 0; n < 4; ++n) {
;               const int chunk = (wc * 8 + n * 2 + (fre >> 3)) ^ (fqe << 1);
;               d[chunk * 8] = f2bf(acc[m][n][j] * rs);
;             }
;           }
;           __builtin_amdgcn_sched_barrier(0);
;         }
	ds_read_b128 v[64:67], v131 offset:256
	s_waitcnt lgkmcnt(0)
	v_mul_f32_e32 v48, v48, v64
	v_cvt_pk_bf16_f32 v48, v48, s0
	v_mul_f32_e32 v56, v56, v64
	v_mul_f32_e32 v52, v52, v64
	ds_write_b16 v112, v48
	v_mul_f32_e32 v48, v61, v65
	v_cvt_pk_bf16_f32 v56, v56, s0
	v_cvt_pk_bf16_f32 v52, v52, s0
	v_cvt_pk_bf16_f32 v48, v48, s0
	v_mul_f32_e32 v60, v60, v64
	ds_write_b16 v120, v56
	ds_write_b16 v116, v52
	ds_write_b16 v124, v48 offset:512
	v_mul_f32_e32 v48, v57, v65
	v_cvt_pk_bf16_f32 v60, v60, s0
	v_cvt_pk_bf16_f32 v48, v48, s0
	ds_write_b16 v124, v60
	ds_write_b16 v120, v48 offset:512
	v_mul_f32_e32 v48, v53, v65
	v_cvt_pk_bf16_f32 v48, v48, s0
	ds_write_b16 v116, v48 offset:512
	v_mul_f32_e32 v48, v49, v65
	v_cvt_pk_bf16_f32 v48, v48, s0
	ds_write_b16 v112, v48 offset:512
	v_mul_f32_e32 v48, v62, v66
	v_cvt_pk_bf16_f32 v48, v48, s0
	ds_write_b16 v124, v48 offset:1024
	v_mul_f32_e32 v48, v58, v66
	v_cvt_pk_bf16_f32 v48, v48, s0
	ds_write_b16 v120, v48 offset:1024
	v_mul_f32_e32 v48, v54, v66
	v_cvt_pk_bf16_f32 v48, v48, s0
	ds_write_b16 v116, v48 offset:1024
	v_mul_f32_e32 v48, v50, v66
	v_cvt_pk_bf16_f32 v48, v48, s0
	ds_write_b16 v112, v48 offset:1024
	v_mul_f32_e32 v48, v63, v67
	v_cvt_pk_bf16_f32 v48, v48, s0
	ds_write_b16 v124, v48 offset:1536
	v_mul_f32_e32 v48, v59, v67
	v_cvt_pk_bf16_f32 v48, v48, s0
	ds_write_b16 v120, v48 offset:1536
	v_mul_f32_e32 v48, v55, v67
	v_cvt_pk_bf16_f32 v48, v48, s0
	ds_write_b16 v116, v48 offset:1536
	v_mul_f32_e32 v48, v51, v67
	v_cvt_pk_bf16_f32 v48, v48, s0
	ds_write_b16 v112, v48 offset:1536
	ds_read_b128 v[48:51], v131 offset:320
	s_waitcnt lgkmcnt(0)
	v_mul_f32_e32 v44, v44, v48
	v_mul_f32_e32 v32, v32, v48
	v_mul_f32_e32 v40, v40, v48
	v_cvt_pk_bf16_f32 v44, v44, s0
	v_cvt_pk_bf16_f32 v32, v32, s0
	v_mul_f32_e32 v36, v36, v48
	v_cvt_pk_bf16_f32 v40, v40, s0
	ds_write_b16 v124, v44 offset:8192
	ds_write_b16 v120, v40 offset:8192
	ds_write_b16 v112, v32 offset:8192
	v_mul_f32_e32 v32, v45, v49
	v_cvt_pk_bf16_f32 v36, v36, s0
	v_cvt_pk_bf16_f32 v32, v32, s0
	ds_write_b16 v116, v36 offset:8192
	ds_write_b16 v124, v32 offset:8704
	v_mul_f32_e32 v32, v41, v49
	v_cvt_pk_bf16_f32 v32, v32, s0
	ds_write_b16 v120, v32 offset:8704
	v_mul_f32_e32 v32, v37, v49
	v_cvt_pk_bf16_f32 v32, v32, s0
	ds_write_b16 v116, v32 offset:8704
	v_mul_f32_e32 v32, v33, v49
	v_cvt_pk_bf16_f32 v32, v32, s0
	ds_write_b16 v112, v32 offset:8704
	v_mul_f32_e32 v32, v46, v50
	v_cvt_pk_bf16_f32 v32, v32, s0
	ds_write_b16 v124, v32 offset:9216
	v_mul_f32_e32 v32, v42, v50
	v_cvt_pk_bf16_f32 v32, v32, s0
	ds_write_b16 v120, v32 offset:9216
	v_mul_f32_e32 v32, v38, v50
	v_cvt_pk_bf16_f32 v32, v32, s0
	ds_write_b16 v116, v32 offset:9216
	v_mul_f32_e32 v32, v34, v50
	v_cvt_pk_bf16_f32 v32, v32, s0
	ds_write_b16 v112, v32 offset:9216
	v_mul_f32_e32 v32, v47, v51
	v_cvt_pk_bf16_f32 v32, v32, s0
	ds_write_b16 v124, v32 offset:9728
	v_mul_f32_e32 v32, v43, v51
	v_cvt_pk_bf16_f32 v32, v32, s0
	ds_write_b16 v120, v32 offset:9728
	v_mul_f32_e32 v32, v39, v51
	v_cvt_pk_bf16_f32 v32, v32, s0
	ds_write_b16 v116, v32 offset:9728
	v_mul_f32_e32 v32, v35, v51
	v_cvt_pk_bf16_f32 v32, v32, s0
	ds_write_b16 v112, v32 offset:9728
	ds_read_b128 v[32:35], v131 offset:384
	s_waitcnt lgkmcnt(0)
	v_mul_f32_e32 v28, v28, v32
	v_mul_f32_e32 v16, v16, v32
	v_mul_f32_e32 v24, v24, v32
	v_cvt_pk_bf16_f32 v28, v28, s0
	v_cvt_pk_bf16_f32 v16, v16, s0
	v_mul_f32_e32 v20, v20, v32
	v_cvt_pk_bf16_f32 v24, v24, s0
	ds_write_b16 v124, v28 offset:16384
	ds_write_b16 v120, v24 offset:16384
	ds_write_b16 v112, v16 offset:16384
	v_mul_f32_e32 v16, v29, v33
	v_cvt_pk_bf16_f32 v20, v20, s0
	v_cvt_pk_bf16_f32 v16, v16, s0
	ds_write_b16 v116, v20 offset:16384
	ds_write_b16 v124, v16 offset:16896
	v_mul_f32_e32 v16, v25, v33
	v_cvt_pk_bf16_f32 v16, v16, s0
	ds_write_b16 v120, v16 offset:16896
	v_mul_f32_e32 v16, v21, v33
	v_cvt_pk_bf16_f32 v16, v16, s0
	ds_write_b16 v116, v16 offset:16896
	v_mul_f32_e32 v16, v17, v33
	v_cvt_pk_bf16_f32 v16, v16, s0
	ds_write_b16 v112, v16 offset:16896
	v_mul_f32_e32 v16, v30, v34
	v_cvt_pk_bf16_f32 v16, v16, s0
	ds_write_b16 v124, v16 offset:17408
	v_mul_f32_e32 v16, v26, v34
	v_cvt_pk_bf16_f32 v16, v16, s0
	ds_write_b16 v120, v16 offset:17408
	v_mul_f32_e32 v16, v22, v34
	v_cvt_pk_bf16_f32 v16, v16, s0
	ds_write_b16 v116, v16 offset:17408
	v_mul_f32_e32 v16, v18, v34
	v_cvt_pk_bf16_f32 v16, v16, s0
	ds_write_b16 v112, v16 offset:17408
	v_mul_f32_e32 v16, v31, v35
	v_cvt_pk_bf16_f32 v16, v16, s0
	ds_write_b16 v124, v16 offset:17920
	v_mul_f32_e32 v16, v27, v35
	v_cvt_pk_bf16_f32 v16, v16, s0
	ds_write_b16 v120, v16 offset:17920
	v_mul_f32_e32 v16, v23, v35
	v_cvt_pk_bf16_f32 v16, v16, s0
	ds_write_b16 v116, v16 offset:17920
	v_mul_f32_e32 v16, v19, v35
	v_cvt_pk_bf16_f32 v16, v16, s0
	ds_write_b16 v112, v16 offset:17920
	ds_read_b128 v[16:19], v131 offset:448
	s_waitcnt lgkmcnt(0)
	v_mul_f32_e32 v12, v12, v16
	v_mul_f32_e32 v0, v0, v16
	v_mul_f32_e32 v8, v8, v16
	v_cvt_pk_bf16_f32 v12, v12, s0
	v_cvt_pk_bf16_f32 v0, v0, s0
	v_mul_f32_e32 v4, v4, v16
	v_cvt_pk_bf16_f32 v8, v8, s0
	ds_write_b16 v124, v12 offset:24576
	ds_write_b16 v120, v8 offset:24576
	ds_write_b16 v112, v0 offset:24576
	v_mul_f32_e32 v0, v13, v17
	v_cvt_pk_bf16_f32 v4, v4, s0
	v_cvt_pk_bf16_f32 v0, v0, s0
	ds_write_b16 v116, v4 offset:24576
	ds_write_b16 v124, v0 offset:25088
	v_mul_f32_e32 v0, v9, v17
	v_cvt_pk_bf16_f32 v0, v0, s0
	ds_write_b16 v120, v0 offset:25088
	v_mul_f32_e32 v0, v5, v17
	v_cvt_pk_bf16_f32 v0, v0, s0
	ds_write_b16 v116, v0 offset:25088
	v_mul_f32_e32 v0, v1, v17
	v_cvt_pk_bf16_f32 v0, v0, s0
	ds_write_b16 v112, v0 offset:25088
	v_mul_f32_e32 v0, v14, v18
	v_cvt_pk_bf16_f32 v0, v0, s0
	ds_write_b16 v124, v0 offset:25600
	v_mul_f32_e32 v0, v10, v18
	v_cvt_pk_bf16_f32 v0, v0, s0
	ds_write_b16 v120, v0 offset:25600
	v_mul_f32_e32 v0, v6, v18
	v_cvt_pk_bf16_f32 v0, v0, s0
	ds_write_b16 v116, v0 offset:25600
	v_mul_f32_e32 v0, v2, v18
	v_cvt_pk_bf16_f32 v0, v0, s0
	ds_write_b16 v112, v0 offset:25600
	v_mul_f32_e32 v0, v15, v19
	v_cvt_pk_bf16_f32 v0, v0, s0
	ds_write_b16 v124, v0 offset:26112
	v_mul_f32_e32 v0, v11, v19
	v_cvt_pk_bf16_f32 v0, v0, s0
	ds_write_b16 v120, v0 offset:26112
	v_mul_f32_e32 v0, v7, v19
	v_cvt_pk_bf16_f32 v0, v0, s0
	ds_write_b16 v116, v0 offset:26112
	v_mul_f32_e32 v0, v3, v19
	v_cvt_pk_bf16_f32 v0, v0, s0
	ds_write_b16 v112, v0 offset:26112
	s_waitcnt lgkmcnt(0)
	s_barrier
; template <int EPI>
; __device__ __forceinline__ void gemm_phase(const Params& p, const u16* __restrict__ A, const u16* __restrict__ Bt, int K, int nN,
;                            u16* __restrict__ Cout, int ldc) {
;     ...
;         __syncthreads();
; #pragma unroll
;         for (int it = 0; it < 8; ++it) {
;           const int id = it * 512 + tide, r = id >> 5, ck = id & 31;
;           const uint4 v = *(const uint4*)(stg + r * 256 + ((ck ^ (((r >> 2) & 3) << 1)) * 8));
;           const int grow = brow + (r >> 6) * 128 + half * 64 + (r & 63);
;           if (EPI == EPI_WIN) { typedef __attribute__((ext_vector_type(4))) unsigned u32x4_; const u32x4_ t_ = {v.x, v.y, v.z, v.w};
;             __builtin_nontemporal_store(t_, (u32x4_*)(Cout + (unsigned)grow * (unsigned)ldc + (unsigned)(bcol + ck * 8))); }
;           else *(uint4*)(Cout + (unsigned)grow * (unsigned)ldc + (unsigned)(bcol + ck * 8)) = v;
;         }
;         asm volatile("s_waitcnt lgkmcnt(0)" ::: "memory"); __builtin_amdgcn_s_barrier();
	s_or_b32 s2, s16, 64
	ds_read_b128 v[0:3], v130
	v_add_u32_e32 v4, s2, v70
	v_or_b32_e32 v4, v4, v71
	v_mul_lo_u32 v4, v4, s58
	v_mov_b32_e32 v5, v172
	v_lshl_add_u64 v[4:5], v[4:5], 1, v[128:129]
	s_waitcnt lgkmcnt(0)
	global_store_dwordx4 v[4:5], v[0:3], off sc0 sc1 nt
	ds_read_b128 v[0:3], v72
	v_add_u32_e32 v4, s2, v73
	v_or_b32_e32 v4, v4, v74
	v_mul_lo_u32 v4, v4, s58
	v_mov_b32_e32 v5, v172
	v_lshl_add_u64 v[4:5], v[4:5], 1, v[128:129]
	s_waitcnt lgkmcnt(0)
	global_store_dwordx4 v[4:5], v[0:3], off sc0 sc1 nt
	ds_read_b128 v[0:3], v75
	v_add_u32_e32 v4, s2, v76
	v_or_b32_e32 v4, v4, v77
	v_mul_lo_u32 v4, v4, s58
	v_mov_b32_e32 v5, v172
	v_lshl_add_u64 v[4:5], v[4:5], 1, v[128:129]
	s_waitcnt lgkmcnt(0)
	global_store_dwordx4 v[4:5], v[0:3], off sc0 sc1 nt
	ds_read_b128 v[0:3], v78
	v_add_u32_e32 v4, s2, v79
	v_or_b32_e32 v4, v4, v80
	v_mul_lo_u32 v4, v4, s58
	v_mov_b32_e32 v5, v172
	v_lshl_add_u64 v[4:5], v[4:5], 1, v[128:129]
	s_waitcnt lgkmcnt(0)
	global_store_dwordx4 v[4:5], v[0:3], off sc0 sc1 nt
	ds_read_b128 v[0:3], v81
	v_add_u32_e32 v4, s2, v82
	v_or_b32_e32 v4, v4, v83
	v_mul_lo_u32 v4, v4, s58
	v_mov_b32_e32 v5, v172
	v_lshl_add_u64 v[4:5], v[4:5], 1, v[128:129]
	s_waitcnt lgkmcnt(0)
	global_store_dwordx4 v[4:5], v[0:3], off sc0 sc1 nt
	ds_read_b128 v[0:3], v84
	v_add_u32_e32 v4, s2, v85
	v_or_b32_e32 v4, v4, v86
	v_mul_lo_u32 v4, v4, s58
	v_mov_b32_e32 v5, v172
	v_lshl_add_u64 v[4:5], v[4:5], 1, v[128:129]
	s_waitcnt lgkmcnt(0)
	global_store_dwordx4 v[4:5], v[0:3], off sc0 sc1 nt
	ds_read_b128 v[0:3], v87
	v_add_u32_e32 v4, s2, v88
	v_or_b32_e32 v4, v4, v89
	v_mul_lo_u32 v4, v4, s58
	v_mov_b32_e32 v5, v172
	v_lshl_add_u64 v[4:5], v[4:5], 1, v[128:129]
	s_waitcnt lgkmcnt(0)
	global_store_dwordx4 v[4:5], v[0:3], off sc0 sc1 nt
	ds_read_b128 v[0:3], v90
	v_add_u32_e32 v4, s2, v91
	v_or_b32_e32 v4, v4, v92
	v_mul_lo_u32 v4, v4, s58
	v_mov_b32_e32 v5, v172
	v_lshl_add_u64 v[4:5], v[4:5], 1, v[128:129]
	s_waitcnt lgkmcnt(0)
	global_store_dwordx4 v[4:5], v[0:3], off sc0 sc1 nt
	s_waitcnt lgkmcnt(0)
	s_mov_b64 s[34:35], -1
	s_and_b64 vcc, exec, s[14:15]
	s_barrier
	s_cbranch_vccnz .LBB0_881

; __device__ __forceinline__ float bf2f(u16 h) { return __uint_as_float(((unsigned)h) << 16); }
; __device__ __forceinline__ int bid_() { int b = blockIdx.x; asm volatile("" : "+s"(b)); return b; }
; __device__ __forceinline__ void phase_resid(const Params& p, const float* __restrict__ gpost, float scale, const float* __restrict__ wdt) {
;     ...
;   for (int row0 = bid_() * 8 + wid; row0 < NTOK / 2; row0 += gridDim.x * 8) {
;     uint2 fv[2][4];
;     float4 xv[2][4];
;     float sf[2] = {0.f, 0.f};
; #pragma unroll
;     for (int r = 0; r < 2; ++r) {
;       const long row = row0 + r * (NTOK / 2);
; #pragma unroll
;       for (int i = 0; i < 4; ++i) {
;         { typedef __attribute__((ext_vector_type(2))) unsigned u32x2_;
;           const u32x2_ t_ = __builtin_nontemporal_load((const u32x2_*)(L_xb + row * DM + i * 256 + lane * 4));
;           fv[r][i] = make_uint2(t_[0], t_[1]); }
;         { const f32x4 t_ = __builtin_nontemporal_load((const f32x4*)(L_out + row * DM + i * 256 + lane * 4));
;           xv[r][i] = make_float4(t_[0], t_[1], t_[2], t_[3]); }
;       }
;     }
; #pragma unroll
;     for (int r = 0; r < 2; ++r) {
; #pragma unroll
;       for (int i = 0; i < 4; ++i) {
;         const float a = bf2f((u16)(fv[r][i].x & 0xffff)), b = bf2f((u16)(fv[r][i].x >> 16));
;         const float c = bf2f((u16)(fv[r][i].y & 0xffff)), d = bf2f((u16)(fv[r][i].y >> 16));
;         sf[r] += a * a + b * b + c * c + d * d;
;       }
;       sf[r] = wave_sum(sf[r]);
;     }
.LBB0_1055:
	v_ashrrev_i32_e32 v129, 31, v128
	v_lshlrev_b64 v[16:17], 11, v[128:129]
	v_lshl_add_u64 v[58:59], v[130:131], 0, v[16:17]
	v_add_u32_e32 v178, 0x4000, v128
	global_load_dwordx2 v[24:25], v[58:59], off nt
	global_load_dwordx2 v[26:27], v[58:59], off offset:512 nt
	global_load_dwordx2 v[28:29], v[58:59], off offset:1024 nt
	v_ashrrev_i32_e32 v179, 31, v178
	global_load_dwordx2 v[30:31], v[58:59], off offset:1536 nt
	v_lshlrev_b64 v[16:17], 11, v[178:179]
	v_lshl_add_u64 v[56:57], v[130:131], 0, v[16:17]
	global_load_dwordx2 v[40:41], v[56:57], off nt
	global_load_dwordx2 v[42:43], v[56:57], off offset:512 nt
	global_load_dwordx2 v[44:45], v[56:57], off offset:1024 nt
	global_load_dwordx2 v[46:47], v[56:57], off offset:1536 nt
	v_lshlrev_b64 v[16:17], 12, v[128:129]
	v_lshl_add_u64 v[60:61], v[132:133], 0, v[16:17]
	global_load_dwordx4 v[32:35], v[60:61], off nt
	global_load_dwordx4 v[36:39], v[60:61], off offset:1024 nt
	global_load_dwordx4 v[20:23], v[60:61], off offset:2048 nt
	global_load_dwordx4 v[16:19], v[60:61], off offset:3072 nt
	v_lshlrev_b64 v[216:217], 12, v[178:179]
	v_lshl_add_u64 v[216:217], v[132:133], 0, v[216:217]
	global_load_dwordx4 v[200:203], v[216:217], off nt
	global_load_dwordx4 v[204:207], v[216:217], off offset:1024 nt
	global_load_dwordx4 v[208:211], v[216:217], off offset:2048 nt
	global_load_dwordx4 v[212:215], v[216:217], off offset:3072 nt
	s_waitcnt vmcnt(0) lgkmcnt(0)
	v_lshlrev_b32_e32 v80, 16, v24
	v_and_b32_e32 v81, 0xffff0000, v24
	v_lshlrev_b32_e32 v84, 16, v26
	v_and_b32_e32 v85, 0xffff0000, v26
	v_lshlrev_b32_e32 v82, 16, v25
	v_and_b32_e32 v83, 0xffff0000, v25
	v_lshlrev_b32_e32 v86, 16, v27
	v_and_b32_e32 v87, 0xffff0000, v27
	v_lshlrev_b32_e32 v88, 16, v28
	v_and_b32_e32 v89, 0xffff0000, v28
	v_lshlrev_b32_e32 v90, 16, v29
	v_and_b32_e32 v91, 0xffff0000, v29
	v_pk_mul_f32 v[24:25], v[80:81], v[80:81]
	v_pk_mul_f32 v[28:29], v[84:85], v[84:85]
	v_lshlrev_b32_e32 v92, 16, v30
	v_and_b32_e32 v93, 0xffff0000, v30
	v_lshlrev_b32_e32 v94, 16, v31
	v_and_b32_e32 v95, 0xffff0000, v31
	v_lshlrev_b32_e32 v78, 16, v40
	v_and_b32_e32 v79, 0xffff0000, v40
	v_lshlrev_b32_e32 v76, 16, v41
	v_and_b32_e32 v77, 0xffff0000, v41
	v_pk_mul_f32 v[26:27], v[82:83], v[82:83]
	v_pk_mul_f32 v[30:31], v[86:87], v[86:87]
	v_pk_mul_f32 v[40:41], v[88:89], v[88:89]
	v_add_f32_e32 v28, v28, v29
	v_add_f32_e32 v24, v24, v25
	v_lshlrev_b32_e32 v74, 16, v42
	v_and_b32_e32 v75, 0xffff0000, v42
	v_lshlrev_b32_e32 v72, 16, v43
	v_and_b32_e32 v73, 0xffff0000, v43
	v_lshlrev_b32_e32 v70, 16, v44
	v_and_b32_e32 v71, 0xffff0000, v44
	v_lshlrev_b32_e32 v68, 16, v45
	v_and_b32_e32 v69, 0xffff0000, v45
	v_pk_mul_f32 v[42:43], v[90:91], v[90:91]
	v_pk_mul_f32 v[44:45], v[92:93], v[92:93]
	v_add_f32_e32 v25, v40, v41
	v_add_f32_e32 v28, v30, v28
	v_add_f32_e32 v24, v26, v24
	v_lshlrev_b32_e32 v64, 16, v46
	v_and_b32_e32 v65, 0xffff0000, v46
	v_lshlrev_b32_e32 v62, 16, v47
	v_and_b32_e32 v63, 0xffff0000, v47
	v_pk_mul_f32 v[46:47], v[94:95], v[94:95]
	v_add_f32_e32 v29, v44, v45
	v_add_f32_e32 v25, v42, v25
	v_add_f32_e32 v28, v31, v28
	v_add_f32_e32 v24, v27, v24
	v_add_f32_e32 v26, v46, v29
	v_add_f32_e32 v25, v43, v25
	v_add_f32_e32 v24, v24, v28
	v_add_f32_e32 v24, v24, v25
	v_add_f32_e32 v25, v47, v26
	v_add_f32_e32 v24, v24, v25
	ds_swizzle_b32 v25, v24 offset:swizzle(SWAP,1)
	v_pk_mul_f32 v[48:49], v[78:79], v[78:79]
	v_pk_mul_f32 v[52:53], v[74:75], v[74:75]
	v_pk_mul_f32 v[50:51], v[76:77], v[76:77]
	v_pk_mul_f32 v[54:55], v[72:73], v[72:73]
	v_pk_mul_f32 v[66:67], v[70:71], v[70:71]
	v_add_f32_e32 v40, v52, v53
	v_add_f32_e32 v41, v48, v49
	v_pk_mul_f32 v[96:97], v[68:69], v[68:69]
	v_add_f32_e32 v44, v66, v67
	v_add_f32_e32 v29, v54, v40
	v_add_f32_e32 v30, v50, v41
	s_waitcnt lgkmcnt(0)
	v_add_f32_e32 v24, v24, v25
	v_add_f32_e32 v27, v55, v29
	v_add_f32_e32 v29, v51, v30
	v_add_f32_e32 v26, v96, v44
	ds_swizzle_b32 v25, v24 offset:swizzle(SWAP,2)
	v_pk_mul_f32 v[98:99], v[64:65], v[64:65]
	v_add_f32_e32 v27, v29, v27
	v_add_f32_e32 v26, v97, v26
	v_pk_mul_f32 v[100:101], v[62:63], v[62:63]
	v_add_f32_e32 v26, v27, v26
	v_add_f32_e32 v27, v98, v99
	v_add_f32_e32 v27, v100, v27
	v_add_f32_e32 v27, v101, v27
	v_add_f32_e32 v26, v26, v27
	s_waitcnt lgkmcnt(0)
	v_add_f32_e32 v28, v24, v25
	ds_swizzle_b32 v27, v26 offset:swizzle(SWAP,1)
	ds_swizzle_b32 v29, v28 offset:swizzle(SWAP,4)
	v_lshlrev_b64 v[24:25], 12, v[178:179]
	v_lshl_add_u64 v[66:67], v[132:133], 0, v[24:25]
	v_mov_b64_e32 v[52:53], v[200:201]
	v_mov_b64_e32 v[54:55], v[202:203]
	v_mov_b64_e32 v[48:49], v[204:205]
	v_mov_b64_e32 v[50:51], v[206:207]
	s_waitcnt lgkmcnt(0)
	v_add_f32_e32 v24, v26, v27
	v_add_f32_e32 v26, v28, v29
	ds_swizzle_b32 v25, v24 offset:swizzle(SWAP,2)
	ds_swizzle_b32 v27, v26 offset:swizzle(SWAP,8)
	s_waitcnt lgkmcnt(0)
	v_add_f32_e32 v40, v24, v25
	v_add_f32_e32 v42, v26, v27
	v_mov_b64_e32 v[24:25], v[208:209]
	v_mov_b64_e32 v[26:27], v[210:211]
	v_mov_b64_e32 v[28:29], v[212:213]
	v_mov_b64_e32 v[30:31], v[214:215]
	ds_swizzle_b32 v43, v42 offset:swizzle(SWAP,16)
	ds_swizzle_b32 v41, v40 offset:swizzle(SWAP,4)
	s_waitcnt lgkmcnt(0)
	v_add_f32_e32 v42, v42, v43
	s_nop 0
	v_readlane_b32 s24, v42, 32
	v_readlane_b32 s8, v42, 0
	v_add_f32_e32 v40, v40, v41
	v_mov_b32_e32 v42, s24
	v_add_f32_e32 v42, s8, v42
	v_fmamk_f32 v42, v42, 0x3a800000, v183
	ds_swizzle_b32 v41, v40 offset:swizzle(SWAP,8)
	v_rsq_f32_e32 v42, v42
	s_waitcnt lgkmcnt(0)
; __device__ __forceinline__ float bf2f(u16 h) { return __uint_as_float(((unsigned)h) << 16); }
; __device__ __forceinline__ float rsq_(float x) { return __builtin_amdgcn_rsqf(x); }
; __device__ __forceinline__ void phase_resid(const Params& p, const float* __restrict__ gpost, float scale, const float* __restrict__ wdt) {
;     ...
; #pragma unroll
;     for (int r = 0; r < 2; ++r) {
;       const long row = row0 + r * (NTOK / 2);
;       const float rs = rsq_(sf[r] * (1.f / DM) + EPS) * scale;
;       float ss = 0.f;
; #pragma unroll
;       for (int i = 0; i < 4; ++i) {
;         const int c = i * 256 + lane * 4;
;         float4 x4 = xv[r][i];
;         const float4 gv = *(const float4*)(gpost + c);
;         x4.x += rs * bf2f((u16)(fv[r][i].x & 0xffff)) * gv.x;
;         x4.y += rs * bf2f((u16)(fv[r][i].x >> 16)) * gv.y;
;         x4.z += rs * bf2f((u16)(fv[r][i].y & 0xffff)) * gv.z;
;         x4.w += rs * bf2f((u16)(fv[r][i].y >> 16)) * gv.w;
;         { const f32x4 t_ = {x4.x, x4.y, x4.z, x4.w}; __builtin_nontemporal_store(t_, (f32x4*)(L_out + row * DM + c)); }
;         xv[r][i] = x4;
;         uint2 o; o.x = pack2(x4.x, x4.y); o.y = pack2(x4.z, x4.w);
;         *(uint2*)(L_xb + row * DM + c) = o;
;         ss += x4.x * x4.x + x4.y * x4.y + x4.z * x4.z + x4.w * x4.w;
;       }
;       ss = wave_sum(ss);
;       if (lane == 0) L_ssx[row] = ss;
;     }
	v_add_f32_e32 v96, v40, v41
	v_mul_f32_e32 v46, v173, v42
	v_pk_mul_f32 v[40:41], v[46:47], v[80:81] op_sel_hi:[0,1]
	v_pk_fma_f32 v[32:33], v[0:1], v[40:41], v[32:33]
	v_pk_mul_f32 v[40:41], v[46:47], v[82:83] op_sel_hi:[0,1]
	v_pk_fma_f32 v[34:35], v[2:3], v[40:41], v[34:35]
	v_pk_mul_f32 v[40:41], v[46:47], v[84:85] op_sel_hi:[0,1]
	v_pk_fma_f32 v[36:37], v[4:5], v[40:41], v[36:37]
	v_pk_mul_f32 v[40:41], v[46:47], v[86:87] op_sel_hi:[0,1]
	v_pk_fma_f32 v[38:39], v[6:7], v[40:41], v[38:39]
	v_pk_mul_f32 v[40:41], v[46:47], v[88:89] op_sel_hi:[0,1]
	v_pk_mul_f32 v[80:81], v[32:33], v[32:33]
	v_pk_mul_f32 v[84:85], v[36:37], v[36:37]
	v_pk_fma_f32 v[40:41], v[8:9], v[40:41], v[20:21]
	v_pk_mul_f32 v[20:21], v[46:47], v[90:91] op_sel_hi:[0,1]
	v_pk_mul_f32 v[44:45], v[46:47], v[92:93] op_sel_hi:[0,1]
	v_pk_mul_f32 v[82:83], v[34:35], v[34:35]
	v_pk_mul_f32 v[86:87], v[38:39], v[38:39]
	v_pk_fma_f32 v[42:43], v[10:11], v[20:21], v[22:23]
	v_pk_mul_f32 v[20:21], v[40:41], v[40:41]
	v_pk_fma_f32 v[44:45], v[12:13], v[44:45], v[16:17]
	v_pk_mul_f32 v[16:17], v[46:47], v[94:95] op_sel_hi:[0,1]
	v_add_f32_e32 v84, v84, v85
	v_add_f32_e32 v80, v80, v81
	v_pk_mul_f32 v[22:23], v[42:43], v[42:43]
	v_pk_fma_f32 v[46:47], v[14:15], v[16:17], v[18:19]
	v_pk_mul_f32 v[16:17], v[44:45], v[44:45]
	v_add_f32_e32 v84, v86, v84
	v_add_f32_e32 v80, v82, v80
	v_add_f32_e32 v20, v20, v21
	v_pk_mul_f32 v[18:19], v[46:47], v[46:47]
	v_add_f32_e32 v84, v87, v84
	v_add_f32_e32 v80, v83, v80
	v_add_f32_e32 v20, v22, v20
	v_add_f32_e32 v16, v16, v17
	v_add_f32_e32 v80, v80, v84
	v_add_f32_e32 v20, v23, v20
	v_add_f32_e32 v16, v18, v16
	v_add_f32_e32 v20, v20, v80
	v_add_f32_e32 v16, v19, v16
	v_add_f32_e32 v180, v16, v20
	ds_swizzle_b32 v16, v180 offset:swizzle(SWAP,1)
	ds_swizzle_b32 v97, v96 offset:swizzle(SWAP,16)
	global_store_dwordx4 v[60:61], v[32:35], off sc0 sc1 nt
	s_waitcnt lgkmcnt(0)
	v_add_f32_e32 v18, v180, v16
	ds_swizzle_b32 v19, v18 offset:swizzle(SWAP,2)
	v_add_f32_e32 v17, v96, v97
	v_cvt_pk_bf16_f32 v16, v32, v33
	v_readlane_b32 s8, v17, 0
	v_readlane_b32 s26, v17, 32
	s_waitcnt lgkmcnt(0)
	v_add_f32_e32 v18, v18, v19
	ds_swizzle_b32 v19, v18 offset:swizzle(SWAP,4)
	v_cvt_pk_bf16_f32 v17, v34, v35
	global_store_dwordx2 v[58:59], v[16:17], off sc0 sc1
	v_cvt_pk_bf16_f32 v16, v36, v37
	v_cvt_pk_bf16_f32 v17, v38, v39
	s_waitcnt lgkmcnt(0)
	v_add_f32_e32 v18, v18, v19
	ds_swizzle_b32 v19, v18 offset:swizzle(SWAP,8)
	global_store_dwordx4 v[60:61], v[36:39], off offset:1024 sc0 sc1 nt
	global_store_dwordx2 v[58:59], v[16:17], off offset:512 sc0 sc1
	v_cvt_pk_bf16_f32 v16, v40, v41
	v_cvt_pk_bf16_f32 v17, v42, v43
	s_waitcnt lgkmcnt(0)
	v_add_f32_e32 v18, v18, v19
	ds_swizzle_b32 v19, v18 offset:swizzle(SWAP,16)
	global_store_dwordx4 v[60:61], v[40:43], off offset:2048 sc0 sc1 nt
	global_store_dwordx2 v[58:59], v[16:17], off offset:1024 sc0 sc1
	v_cvt_pk_bf16_f32 v16, v44, v45
	v_cvt_pk_bf16_f32 v17, v46, v47
	global_store_dwordx4 v[60:61], v[44:47], off offset:3072 sc0 sc1 nt
	global_store_dwordx2 v[58:59], v[16:17], off offset:1536 sc0 sc1
	s_waitcnt lgkmcnt(0)
	v_add_f32_e32 v16, v18, v19
	s_nop 0
	v_readlane_b32 s27, v16, 0
	v_readlane_b32 s28, v16, 32
	s_and_saveexec_b64 s[24:25], s[0:1]
	s_cbranch_execz .LBB0_1057
	v_mov_b32_e32 v18, s28
	v_lshl_add_u64 v[16:17], v[128:129], 2, s[16:17]
	v_add_f32_e32 v18, s27, v18
	global_store_dword v[16:17], v18, off sc0 sc1
.LBB0_1057:
	s_or_b64 exec, exec, s[24:25]
	v_mov_b32_e32 v16, s26
	v_add_f32_e32 v16, s8, v16
	v_fmamk_f32 v16, v16, 0x3a800000, v183
	v_rsq_f32_e32 v16, v16
	s_nop 0
	v_mul_f32_e32 v58, v173, v16
	v_pk_mul_f32 v[16:17], v[58:59], v[78:79] op_sel_hi:[0,1]
	v_pk_mul_f32 v[20:21], v[58:59], v[74:75] op_sel_hi:[0,1]
	v_pk_mul_f32 v[18:19], v[58:59], v[76:77] op_sel_hi:[0,1]
	v_pk_fma_f32 v[16:17], v[0:1], v[16:17], v[52:53]
	v_pk_fma_f32 v[20:21], v[4:5], v[20:21], v[48:49]
	v_pk_mul_f32 v[22:23], v[58:59], v[72:73] op_sel_hi:[0,1]
	v_pk_fma_f32 v[18:19], v[2:3], v[18:19], v[54:55]
	v_pk_mul_f32 v[52:53], v[16:17], v[16:17]
	v_pk_fma_f32 v[22:23], v[6:7], v[22:23], v[50:51]
	v_pk_mul_f32 v[48:49], v[20:21], v[20:21]
	v_pk_mul_f32 v[54:55], v[18:19], v[18:19]
	v_pk_mul_f32 v[50:51], v[22:23], v[22:23]
	v_pk_mul_f32 v[60:61], v[58:59], v[70:71] op_sel_hi:[0,1]
	v_add_f32_e32 v48, v48, v49
	v_add_f32_e32 v49, v52, v53
	v_pk_fma_f32 v[24:25], v[8:9], v[60:61], v[24:25]
	v_pk_mul_f32 v[60:61], v[58:59], v[68:69] op_sel_hi:[0,1]
	v_add_f32_e32 v48, v50, v48
	v_add_f32_e32 v49, v54, v49
	v_pk_fma_f32 v[26:27], v[10:11], v[60:61], v[26:27]
	v_pk_mul_f32 v[60:61], v[24:25], v[24:25]
	v_add_f32_e32 v48, v51, v48
	v_add_f32_e32 v49, v55, v49
	v_pk_mul_f32 v[68:69], v[26:27], v[26:27]
	v_pk_mul_f32 v[64:65], v[58:59], v[64:65] op_sel_hi:[0,1]
	v_add_f32_e32 v48, v49, v48
	v_add_f32_e32 v49, v60, v61
	v_pk_fma_f32 v[28:29], v[12:13], v[64:65], v[28:29]
	v_pk_mul_f32 v[58:59], v[58:59], v[62:63] op_sel_hi:[0,1]
	v_add_f32_e32 v49, v68, v49
	v_pk_fma_f32 v[30:31], v[14:15], v[58:59], v[30:31]
	v_pk_mul_f32 v[58:59], v[28:29], v[28:29]
	v_add_f32_e32 v49, v69, v49
	v_pk_mul_f32 v[62:63], v[30:31], v[30:31]
	v_add_f32_e32 v48, v49, v48
	v_add_f32_e32 v49, v58, v59
	v_add_f32_e32 v49, v62, v49
	v_add_f32_e32 v49, v63, v49
	v_add_f32_e32 v191, v49, v48
	ds_swizzle_b32 v48, v191 offset:swizzle(SWAP,1)
	v_cvt_pk_bf16_f32 v49, v18, v19
	global_store_dwordx4 v[66:67], v[16:19], off sc0 sc1 nt
	s_waitcnt lgkmcnt(0)
	v_add_f32_e32 v50, v191, v48
	ds_swizzle_b32 v51, v50 offset:swizzle(SWAP,2)
	v_cvt_pk_bf16_f32 v48, v16, v17
	global_store_dwordx2 v[56:57], v[48:49], off sc0 sc1
	v_cvt_pk_bf16_f32 v48, v20, v21
	v_cvt_pk_bf16_f32 v49, v22, v23
	s_waitcnt lgkmcnt(0)
	v_add_f32_e32 v50, v50, v51
	ds_swizzle_b32 v51, v50 offset:swizzle(SWAP,4)
	global_store_dwordx4 v[66:67], v[20:23], off offset:1024 sc0 sc1 nt
	global_store_dwordx2 v[56:57], v[48:49], off offset:512 sc0 sc1
	v_cvt_pk_bf16_f32 v48, v24, v25
	v_cvt_pk_bf16_f32 v49, v26, v27
	s_waitcnt lgkmcnt(0)
	v_add_f32_e32 v50, v50, v51
	ds_swizzle_b32 v51, v50 offset:swizzle(SWAP,8)
	global_store_dwordx4 v[66:67], v[24:27], off offset:2048 sc0 sc1 nt
	global_store_dwordx2 v[56:57], v[48:49], off offset:1024 sc0 sc1
	v_cvt_pk_bf16_f32 v48, v28, v29
	v_cvt_pk_bf16_f32 v49, v30, v31
	s_waitcnt lgkmcnt(0)
	v_add_f32_e32 v50, v50, v51
	ds_swizzle_b32 v51, v50 offset:swizzle(SWAP,16)
	global_store_dwordx4 v[66:67], v[28:31], off offset:3072 sc0 sc1 nt
	global_store_dwordx2 v[56:57], v[48:49], off offset:1536 sc0 sc1
	s_waitcnt lgkmcnt(0)
	v_add_f32_e32 v48, v50, v51
	s_nop 0
	v_readlane_b32 s8, v48, 0
	v_readlane_b32 s26, v48, 32
	s_and_saveexec_b64 s[24:25], s[0:1]
	s_cbranch_execz .LBB0_1059
	v_mov_b32_e32 v50, s26
	v_lshl_add_u64 v[48:49], v[178:179], 2, s[16:17]
	v_add_f32_e32 v50, s8, v50
	global_store_dword v[48:49], v50, off sc0 sc1
; __device__ __forceinline__ float rsq_(float x) { return __builtin_amdgcn_rsqf(x); }
; __device__ __forceinline__ void phase_resid(const Params& p, const float* __restrict__ gpost, float scale, const float* __restrict__ wdt) {
;     ...
;     if (wdt) {
; #pragma unroll
;       for (int r = 0; r < 2; ++r) {
;         const long row = row0 + r * (NTOK / 2);
;         float ss = 0.f, d[6] = {0.f, 0.f, 0.f, 0.f, 0.f, 0.f};
; #pragma unroll
;         for (int i = 0; i < 4; ++i) {
;           const int c = i * 256 + lane * 4;
;           const float4 x4 = xv[r][i];
;           ss += x4.x * x4.x + x4.y * x4.y + x4.z * x4.z + x4.w * x4.w;
; #pragma unroll
;           for (int h = 0; h < 6; ++h) {
;             const float4 w4 = *(const float4*)(wdt + h * DM + c);
;             d[h] += x4.x * w4.x + x4.y * w4.y + x4.z * w4.z + x4.w * w4.w;
;           }
;         }
;         ss = wave_sum(ss);
;         const float rsx = rsq_(ss * (1.f / DM) + EPS);
; #pragma unroll
;         for (int h = 0; h < 6; ++h) { const float v = wave_sum(d[h]); if (lane == h) L_dtbuf[row * 8 + h] = v * rsx; }
.LBB0_1059:
	s_or_b64 exec, exec, s[24:25]
	s_and_b64 vcc, exec, s[22:23]
	s_cbranch_vccz .LBB0_1054
	global_load_dwordx4 v[48:51], v[134:135], off
	ds_swizzle_b32 v181, v180 offset:swizzle(SWAP,1)
	s_waitcnt lgkmcnt(0)
	v_add_f32_e32 v180, v180, v181
	ds_swizzle_b32 v181, v180 offset:swizzle(SWAP,2)
	s_waitcnt lgkmcnt(0)
	v_add_f32_e32 v180, v180, v181
	ds_swizzle_b32 v181, v180 offset:swizzle(SWAP,4)
	s_waitcnt lgkmcnt(0)
	v_add_f32_e32 v180, v180, v181
	ds_swizzle_b32 v181, v180 offset:swizzle(SWAP,8)
	s_waitcnt lgkmcnt(0)
	v_add_f32_e32 v180, v180, v181
	ds_swizzle_b32 v181, v180 offset:swizzle(SWAP,16)
	s_waitcnt lgkmcnt(0)
	v_add_f32_e32 v180, v180, v181
	s_nop 0
	v_readlane_b32 s24, v180, 32
	v_readlane_b32 s8, v180, 0
	s_waitcnt vmcnt(0)
	v_mul_f32_e32 v49, v33, v49
	v_fmac_f32_e32 v49, v32, v48
	v_fmac_f32_e32 v49, v34, v50
	v_fmac_f32_e32 v49, v35, v51
	v_add_f32_e32 v60, 0, v49
	global_load_dwordx4 v[96:99], v[136:137], off
	global_load_dwordx4 v[80:83], v[138:139], off
	global_load_dwordx4 v[68:71], v[140:141], off
	global_load_dwordx4 v[56:59], v[142:143], off
	global_load_dwordx4 v[48:51], v[144:145], off
	global_load_dwordx4 v[52:55], v[134:135], off offset:1024
	v_mov_b32_e32 v180, s24
	v_add_f32_e32 v180, s8, v180
	v_fmamk_f32 v180, v180, 0x3a800000, v183
	v_rsq_f32_e32 v192, v180
	v_lshlrev_b64 v[180:181], 5, v[128:129]
	v_lshl_add_u64 v[180:181], s[10:11], 0, v[180:181]
	s_waitcnt vmcnt(0) lgkmcnt(0)
	v_mul_f32_e32 v53, v37, v53
	v_fmac_f32_e32 v53, v36, v52
	v_fmac_f32_e32 v53, v38, v54
	v_fmac_f32_e32 v53, v39, v55
	v_add_f32_e32 v72, v60, v53
	global_load_dwordx4 v[108:111], v[146:147], off
	global_load_dwordx4 v[92:95], v[148:149], off
	global_load_dwordx4 v[76:79], v[150:151], off
	global_load_dwordx4 v[64:67], v[152:153], off
	global_load_dwordx4 v[52:55], v[154:155], off
	global_load_dwordx4 v[60:63], v[134:135], off offset:2048
	s_waitcnt vmcnt(0) lgkmcnt(0)
	v_mul_f32_e32 v61, v41, v61
	v_fmac_f32_e32 v61, v40, v60
	v_fmac_f32_e32 v61, v42, v62
	v_fmac_f32_e32 v61, v43, v63
	v_add_f32_e32 v100, v72, v61
	global_load_dwordx4 v[116:119], v[156:157], off
	global_load_dwordx4 v[104:107], v[158:159], off
	global_load_dwordx4 v[88:91], v[160:161], off
	global_load_dwordx4 v[72:75], v[162:163], off
	global_load_dwordx4 v[60:63], v[164:165], off
	global_load_dwordx4 v[84:87], v[134:135], off offset:3072
	s_waitcnt vmcnt(0) lgkmcnt(0)
	v_mul_f32_e32 v85, v45, v85
	v_fmac_f32_e32 v85, v44, v84
	v_fmac_f32_e32 v85, v46, v86
	v_fmac_f32_e32 v85, v47, v87
	v_add_f32_e32 v193, v100, v85
	global_load_dwordx4 v[124:127], v[166:167], off
	global_load_dwordx4 v[120:123], v[168:169], off
	global_load_dwordx4 v[112:115], v[170:171], off
	global_load_dwordx4 v[100:103], v[174:175], off
	global_load_dwordx4 v[84:87], v[176:177], off
	ds_swizzle_b32 v129, v193 offset:swizzle(SWAP,1)
	s_waitcnt lgkmcnt(0)
	v_add_f32_e32 v129, v193, v129
	ds_swizzle_b32 v193, v129 offset:swizzle(SWAP,2)
	s_waitcnt lgkmcnt(0)
	v_add_f32_e32 v129, v129, v193
	ds_swizzle_b32 v193, v129 offset:swizzle(SWAP,4)
	s_waitcnt lgkmcnt(0)
	v_add_f32_e32 v129, v129, v193
	ds_swizzle_b32 v193, v129 offset:swizzle(SWAP,8)
	s_waitcnt lgkmcnt(0)
	v_add_f32_e32 v129, v129, v193
	ds_swizzle_b32 v193, v129 offset:swizzle(SWAP,16)
	s_waitcnt lgkmcnt(0)
	v_add_f32_e32 v129, v129, v193
	s_nop 0
	v_readlane_b32 s8, v129, 0
	v_readlane_b32 s26, v129, 32
	s_and_saveexec_b64 s[24:25], s[0:1]
	s_cbranch_execz .LBB0_1062
	v_mov_b32_e32 v129, s26
	v_add_f32_e32 v129, s8, v129
	v_mul_f32_e32 v129, v192, v129
	global_store_dword v[180:181], v129, off sc0 sc1
.LBB0_1062:
	s_or_b64 exec, exec, s[24:25]
	v_mul_f32_e32 v97, v33, v97
	v_fmac_f32_e32 v97, v32, v96
	v_fmac_f32_e32 v97, v34, v98
	v_fmac_f32_e32 v97, v35, v99
	v_add_f32_e32 v96, 0, v97
	v_mul_f32_e32 v97, v37, v109
	v_fmac_f32_e32 v97, v36, v108
	v_fmac_f32_e32 v97, v38, v110
	v_fmac_f32_e32 v97, v39, v111
	v_add_f32_e32 v96, v96, v97
	v_mul_f32_e32 v97, v41, v117
	v_fmac_f32_e32 v97, v40, v116
	v_fmac_f32_e32 v97, v42, v118
	v_fmac_f32_e32 v97, v43, v119
	v_add_f32_e32 v96, v96, v97
	s_waitcnt vmcnt(0)
	v_mul_f32_e32 v97, v45, v125
	v_fmac_f32_e32 v97, v44, v124
	v_fmac_f32_e32 v97, v46, v126
	v_fmac_f32_e32 v97, v47, v127
	v_add_f32_e32 v96, v96, v97
	ds_swizzle_b32 v97, v96 offset:swizzle(SWAP,1)
	s_waitcnt lgkmcnt(0)
	v_add_f32_e32 v96, v96, v97
	ds_swizzle_b32 v97, v96 offset:swizzle(SWAP,2)
	s_waitcnt lgkmcnt(0)
	v_add_f32_e32 v96, v96, v97
	ds_swizzle_b32 v97, v96 offset:swizzle(SWAP,4)
	s_waitcnt lgkmcnt(0)
	v_add_f32_e32 v96, v96, v97
	ds_swizzle_b32 v97, v96 offset:swizzle(SWAP,8)
	s_waitcnt lgkmcnt(0)
	v_add_f32_e32 v96, v96, v97
	ds_swizzle_b32 v97, v96 offset:swizzle(SWAP,16)
	s_waitcnt lgkmcnt(0)
	v_add_f32_e32 v96, v96, v97
	s_nop 0
	v_readlane_b32 s8, v96, 0
	v_readlane_b32 s26, v96, 32
	s_and_saveexec_b64 s[24:25], s[2:3]
	s_cbranch_execz .LBB0_1064
	v_mov_b32_e32 v96, s26
	v_add_f32_e32 v96, s8, v96
	v_mul_f32_e32 v96, v192, v96
	global_store_dword v[180:181], v96, off offset:4 sc0 sc1
; __device__ __forceinline__ float rsq_(float x) { return __builtin_amdgcn_rsqf(x); }
; __device__ __forceinline__ void phase_resid(const Params& p, const float* __restrict__ gpost, float scale, const float* __restrict__ wdt) {
;     ...
; #pragma unroll
;           for (int h = 0; h < 6; ++h) {
;             const float4 w4 = *(const float4*)(wdt + h * DM + c);
;             d[h] += x4.x * w4.x + x4.y * w4.y + x4.z * w4.z + x4.w * w4.w;
;           }
;         }
;         ss = wave_sum(ss);
;         const float rsx = rsq_(ss * (1.f / DM) + EPS);
; #pragma unroll
;         for (int h = 0; h < 6; ++h) { const float v = wave_sum(d[h]); if (lane == h) L_dtbuf[row * 8 + h] = v * rsx; }
.LBB0_1064:
	s_or_b64 exec, exec, s[24:25]
	v_mul_f32_e32 v81, v33, v81
	v_fmac_f32_e32 v81, v32, v80
	v_fmac_f32_e32 v81, v34, v82
	v_fmac_f32_e32 v81, v35, v83
	v_add_f32_e32 v80, 0, v81
	v_mul_f32_e32 v81, v37, v93
	v_fmac_f32_e32 v81, v36, v92
	v_fmac_f32_e32 v81, v38, v94
	v_fmac_f32_e32 v81, v39, v95
	v_add_f32_e32 v80, v80, v81
	v_mul_f32_e32 v81, v41, v105
	v_fmac_f32_e32 v81, v40, v104
	v_fmac_f32_e32 v81, v42, v106
	v_fmac_f32_e32 v81, v43, v107
	v_add_f32_e32 v80, v80, v81
	v_mul_f32_e32 v81, v45, v121
	v_fmac_f32_e32 v81, v44, v120
	v_fmac_f32_e32 v81, v46, v122
	v_fmac_f32_e32 v81, v47, v123
	v_add_f32_e32 v80, v80, v81
	ds_swizzle_b32 v81, v80 offset:swizzle(SWAP,1)
	s_waitcnt lgkmcnt(0)
	v_add_f32_e32 v80, v80, v81
	ds_swizzle_b32 v81, v80 offset:swizzle(SWAP,2)
	s_waitcnt lgkmcnt(0)
	v_add_f32_e32 v80, v80, v81
	ds_swizzle_b32 v81, v80 offset:swizzle(SWAP,4)
	s_waitcnt lgkmcnt(0)
	v_add_f32_e32 v80, v80, v81
	ds_swizzle_b32 v81, v80 offset:swizzle(SWAP,8)
	s_waitcnt lgkmcnt(0)
	v_add_f32_e32 v80, v80, v81
	ds_swizzle_b32 v81, v80 offset:swizzle(SWAP,16)
	s_waitcnt lgkmcnt(0)
	v_add_f32_e32 v80, v80, v81
	s_nop 0
	v_readlane_b32 s8, v80, 0
	v_readlane_b32 s26, v80, 32
	s_and_saveexec_b64 s[24:25], s[4:5]
	s_cbranch_execz .LBB0_1066
	v_mov_b32_e32 v80, s26
	v_add_f32_e32 v80, s8, v80
	v_mul_f32_e32 v80, v192, v80
	global_store_dword v[180:181], v80, off offset:8 sc0 sc1
.LBB0_1066:
	s_or_b64 exec, exec, s[24:25]
	v_mul_f32_e32 v69, v33, v69
	v_fmac_f32_e32 v69, v32, v68
	v_fmac_f32_e32 v69, v34, v70
	v_fmac_f32_e32 v69, v35, v71
	v_add_f32_e32 v68, 0, v69
	v_mul_f32_e32 v69, v37, v77
	v_fmac_f32_e32 v69, v36, v76
	v_fmac_f32_e32 v69, v38, v78
	v_fmac_f32_e32 v69, v39, v79
	v_add_f32_e32 v68, v68, v69
	v_mul_f32_e32 v69, v41, v89
	v_fmac_f32_e32 v69, v40, v88
	v_fmac_f32_e32 v69, v42, v90
	v_fmac_f32_e32 v69, v43, v91
	v_add_f32_e32 v68, v68, v69
	v_mul_f32_e32 v69, v45, v113
	v_fmac_f32_e32 v69, v44, v112
	v_fmac_f32_e32 v69, v46, v114
	v_fmac_f32_e32 v69, v47, v115
	v_add_f32_e32 v68, v68, v69
	ds_swizzle_b32 v69, v68 offset:swizzle(SWAP,1)
	s_waitcnt lgkmcnt(0)
	v_add_f32_e32 v68, v68, v69
	ds_swizzle_b32 v69, v68 offset:swizzle(SWAP,2)
	s_waitcnt lgkmcnt(0)
	v_add_f32_e32 v68, v68, v69
	ds_swizzle_b32 v69, v68 offset:swizzle(SWAP,4)
	s_waitcnt lgkmcnt(0)
	v_add_f32_e32 v68, v68, v69
	ds_swizzle_b32 v69, v68 offset:swizzle(SWAP,8)
	s_waitcnt lgkmcnt(0)
	v_add_f32_e32 v68, v68, v69
	ds_swizzle_b32 v69, v68 offset:swizzle(SWAP,16)
	s_waitcnt lgkmcnt(0)
	v_add_f32_e32 v68, v68, v69
	s_nop 0
	v_readlane_b32 s8, v68, 0
	v_readlane_b32 s26, v68, 32
	s_and_saveexec_b64 s[24:25], s[6:7]
	s_cbranch_execz .LBB0_1068
	v_mov_b32_e32 v68, s26
	v_add_f32_e32 v68, s8, v68
	v_mul_f32_e32 v68, v192, v68
	global_store_dword v[180:181], v68, off offset:12 sc0 sc1
.LBB0_1068:
	s_or_b64 exec, exec, s[24:25]
	v_mul_f32_e32 v57, v33, v57
	v_fmac_f32_e32 v57, v32, v56
	v_fmac_f32_e32 v57, v34, v58
	v_fmac_f32_e32 v57, v35, v59
	v_add_f32_e32 v56, 0, v57
	v_mul_f32_e32 v57, v37, v65
	v_fmac_f32_e32 v57, v36, v64
	v_fmac_f32_e32 v57, v38, v66
	v_fmac_f32_e32 v57, v39, v67
	v_add_f32_e32 v56, v56, v57
	v_mul_f32_e32 v57, v41, v73
	v_fmac_f32_e32 v57, v40, v72
	v_fmac_f32_e32 v57, v42, v74
	v_fmac_f32_e32 v57, v43, v75
	v_add_f32_e32 v56, v56, v57
	v_mul_f32_e32 v57, v45, v101
	v_fmac_f32_e32 v57, v44, v100
	v_fmac_f32_e32 v57, v46, v102
	v_fmac_f32_e32 v57, v47, v103
	v_add_f32_e32 v56, v56, v57
	ds_swizzle_b32 v57, v56 offset:swizzle(SWAP,1)
	s_waitcnt lgkmcnt(0)
	v_add_f32_e32 v56, v56, v57
	ds_swizzle_b32 v57, v56 offset:swizzle(SWAP,2)
	s_waitcnt lgkmcnt(0)
	v_add_f32_e32 v56, v56, v57
	ds_swizzle_b32 v57, v56 offset:swizzle(SWAP,4)
	s_waitcnt lgkmcnt(0)
	v_add_f32_e32 v56, v56, v57
	ds_swizzle_b32 v57, v56 offset:swizzle(SWAP,8)
	s_waitcnt lgkmcnt(0)
	v_add_f32_e32 v56, v56, v57
	ds_swizzle_b32 v57, v56 offset:swizzle(SWAP,16)
	s_waitcnt lgkmcnt(0)
	v_add_f32_e32 v56, v56, v57
	s_nop 0
	v_readlane_b32 s8, v56, 0
	v_readlane_b32 s26, v56, 32
	s_and_saveexec_b64 s[24:25], s[12:13]
	s_cbranch_execz .LBB0_1070
	v_mov_b32_e32 v56, s26
	v_add_f32_e32 v56, s8, v56
	v_mul_f32_e32 v56, v192, v56
	global_store_dword v[180:181], v56, off offset:16 sc0 sc1
.LBB0_1070:
	s_or_b64 exec, exec, s[24:25]
	v_mul_f32_e32 v33, v33, v49
	v_fmac_f32_e32 v33, v32, v48
	v_fmac_f32_e32 v33, v34, v50
	v_fmac_f32_e32 v33, v35, v51
	v_add_f32_e32 v32, 0, v33
	v_mul_f32_e32 v33, v37, v53
	v_fmac_f32_e32 v33, v36, v52
	v_fmac_f32_e32 v33, v38, v54
	v_fmac_f32_e32 v33, v39, v55
	v_add_f32_e32 v32, v32, v33
	v_mul_f32_e32 v33, v41, v61
	v_fmac_f32_e32 v33, v40, v60
	v_fmac_f32_e32 v33, v42, v62
	v_fmac_f32_e32 v33, v43, v63
	v_add_f32_e32 v32, v32, v33
	v_mul_f32_e32 v33, v45, v85
	v_fmac_f32_e32 v33, v44, v84
	v_fmac_f32_e32 v33, v46, v86
	v_fmac_f32_e32 v33, v47, v87
	v_add_f32_e32 v32, v32, v33
	ds_swizzle_b32 v33, v32 offset:swizzle(SWAP,1)
	s_waitcnt lgkmcnt(0)
	v_add_f32_e32 v32, v32, v33
	ds_swizzle_b32 v33, v32 offset:swizzle(SWAP,2)
	s_waitcnt lgkmcnt(0)
	v_add_f32_e32 v32, v32, v33
	ds_swizzle_b32 v33, v32 offset:swizzle(SWAP,4)
	s_waitcnt lgkmcnt(0)
	v_add_f32_e32 v32, v32, v33
	ds_swizzle_b32 v33, v32 offset:swizzle(SWAP,8)
	s_waitcnt lgkmcnt(0)
	v_add_f32_e32 v32, v32, v33
	ds_swizzle_b32 v33, v32 offset:swizzle(SWAP,16)
	s_waitcnt lgkmcnt(0)
	v_add_f32_e32 v32, v32, v33
	s_nop 0
	v_readlane_b32 s8, v32, 0
	v_readlane_b32 s26, v32, 32
	s_and_saveexec_b64 s[24:25], s[14:15]
	s_cbranch_execz .LBB0_1072
	v_mov_b32_e32 v32, s26
	v_add_f32_e32 v32, s8, v32
	v_mul_f32_e32 v32, v192, v32
	global_store_dword v[180:181], v32, off offset:20 sc0 sc1
; __device__ __forceinline__ float rsq_(float x) { return __builtin_amdgcn_rsqf(x); }
; __device__ __forceinline__ void phase_resid(const Params& p, const float* __restrict__ gpost, float scale, const float* __restrict__ wdt) {
;     ...
; #pragma unroll
;         for (int i = 0; i < 4; ++i) {
;           const int c = i * 256 + lane * 4;
;           const float4 x4 = xv[r][i];
;           ss += x4.x * x4.x + x4.y * x4.y + x4.z * x4.z + x4.w * x4.w;
; #pragma unroll
;           for (int h = 0; h < 6; ++h) {
;             const float4 w4 = *(const float4*)(wdt + h * DM + c);
;             d[h] += x4.x * w4.x + x4.y * w4.y + x4.z * w4.z + x4.w * w4.w;
;           }
;         }
;         ss = wave_sum(ss);
;         const float rsx = rsq_(ss * (1.f / DM) + EPS);
; #pragma unroll
;         for (int h = 0; h < 6; ++h) { const float v = wave_sum(d[h]); if (lane == h) L_dtbuf[row * 8 + h] = v * rsx; }
.LBB0_1072:
	s_or_b64 exec, exec, s[24:25]
	global_load_dwordx4 v[32:35], v[134:135], off
	ds_swizzle_b32 v112, v191 offset:swizzle(SWAP,1)
	s_waitcnt lgkmcnt(0)
	v_add_f32_e32 v112, v191, v112
	ds_swizzle_b32 v113, v112 offset:swizzle(SWAP,2)
	s_waitcnt lgkmcnt(0)
	v_add_f32_e32 v112, v112, v113
	ds_swizzle_b32 v113, v112 offset:swizzle(SWAP,4)
	s_waitcnt lgkmcnt(0)
	v_add_f32_e32 v112, v112, v113
	ds_swizzle_b32 v113, v112 offset:swizzle(SWAP,8)
	s_waitcnt lgkmcnt(0)
	v_add_f32_e32 v112, v112, v113
	ds_swizzle_b32 v113, v112 offset:swizzle(SWAP,16)
	s_waitcnt lgkmcnt(0)
	v_add_f32_e32 v112, v112, v113
	s_nop 0
	v_readlane_b32 s24, v112, 32
	v_readlane_b32 s8, v112, 0
	s_waitcnt vmcnt(0)
	v_mul_f32_e32 v33, v17, v33
	v_fmac_f32_e32 v33, v16, v32
	v_fmac_f32_e32 v33, v18, v34
	v_fmac_f32_e32 v33, v19, v35
	v_add_f32_e32 v44, 0, v33
	global_load_dwordx4 v[80:83], v[136:137], off
	global_load_dwordx4 v[64:67], v[138:139], off
	global_load_dwordx4 v[52:55], v[140:141], off
	global_load_dwordx4 v[40:43], v[142:143], off
	global_load_dwordx4 v[32:35], v[144:145], off
	global_load_dwordx4 v[36:39], v[134:135], off offset:1024
	v_mov_b32_e32 v112, s24
	v_add_f32_e32 v112, s8, v112
	v_fmamk_f32 v112, v112, 0x3a800000, v183
	v_rsq_f32_e32 v114, v112
	v_lshlrev_b64 v[112:113], 5, v[178:179]
	v_lshl_add_u64 v[112:113], s[10:11], 0, v[112:113]
	s_waitcnt vmcnt(0) lgkmcnt(0)
	v_mul_f32_e32 v37, v21, v37
	v_fmac_f32_e32 v37, v20, v36
	v_fmac_f32_e32 v37, v22, v38
	v_fmac_f32_e32 v37, v23, v39
	v_add_f32_e32 v56, v44, v37
	global_load_dwordx4 v[92:95], v[146:147], off
	global_load_dwordx4 v[76:79], v[148:149], off
	global_load_dwordx4 v[60:63], v[150:151], off
	global_load_dwordx4 v[48:51], v[152:153], off
	global_load_dwordx4 v[36:39], v[154:155], off
	global_load_dwordx4 v[44:47], v[134:135], off offset:2048
	s_waitcnt vmcnt(0) lgkmcnt(0)
	v_mul_f32_e32 v45, v25, v45
	v_fmac_f32_e32 v45, v24, v44
	v_fmac_f32_e32 v45, v26, v46
	v_fmac_f32_e32 v45, v27, v47
	v_add_f32_e32 v84, v56, v45
	global_load_dwordx4 v[100:103], v[156:157], off
	global_load_dwordx4 v[88:91], v[158:159], off
	global_load_dwordx4 v[72:75], v[160:161], off
	global_load_dwordx4 v[56:59], v[162:163], off
	global_load_dwordx4 v[44:47], v[164:165], off
	global_load_dwordx4 v[68:71], v[134:135], off offset:3072
	s_waitcnt vmcnt(0) lgkmcnt(0)
	v_mul_f32_e32 v69, v29, v69
	v_fmac_f32_e32 v69, v28, v68
	v_fmac_f32_e32 v69, v30, v70
	v_fmac_f32_e32 v69, v31, v71
	v_add_f32_e32 v115, v84, v69
	global_load_dwordx4 v[108:111], v[166:167], off
	global_load_dwordx4 v[104:107], v[168:169], off
	global_load_dwordx4 v[96:99], v[170:171], off
	global_load_dwordx4 v[84:87], v[174:175], off
	global_load_dwordx4 v[68:71], v[176:177], off
	ds_swizzle_b32 v116, v115 offset:swizzle(SWAP,1)
	s_waitcnt lgkmcnt(0)
	v_add_f32_e32 v115, v115, v116
	ds_swizzle_b32 v116, v115 offset:swizzle(SWAP,2)
	s_waitcnt lgkmcnt(0)
	v_add_f32_e32 v115, v115, v116
	ds_swizzle_b32 v116, v115 offset:swizzle(SWAP,4)
	s_waitcnt lgkmcnt(0)
	v_add_f32_e32 v115, v115, v116
	ds_swizzle_b32 v116, v115 offset:swizzle(SWAP,8)
	s_waitcnt lgkmcnt(0)
	v_add_f32_e32 v115, v115, v116
	ds_swizzle_b32 v116, v115 offset:swizzle(SWAP,16)
	s_waitcnt lgkmcnt(0)
	v_add_f32_e32 v115, v115, v116
	s_nop 0
	v_readlane_b32 s8, v115, 0
	v_readlane_b32 s26, v115, 32
	s_and_saveexec_b64 s[24:25], s[0:1]
	s_cbranch_execz .LBB0_1074
	v_mov_b32_e32 v115, s26
	v_add_f32_e32 v115, s8, v115
	v_mul_f32_e32 v115, v114, v115
	global_store_dword v[112:113], v115, off sc0 sc1
.LBB0_1074:
	s_or_b64 exec, exec, s[24:25]
	v_mul_f32_e32 v81, v17, v81
	v_fmac_f32_e32 v81, v16, v80
	v_fmac_f32_e32 v81, v18, v82
	v_fmac_f32_e32 v81, v19, v83
	v_add_f32_e32 v80, 0, v81
	v_mul_f32_e32 v81, v21, v93
	v_fmac_f32_e32 v81, v20, v92
	v_fmac_f32_e32 v81, v22, v94
	v_fmac_f32_e32 v81, v23, v95
	v_add_f32_e32 v80, v80, v81
	v_mul_f32_e32 v81, v25, v101
	v_fmac_f32_e32 v81, v24, v100
	v_fmac_f32_e32 v81, v26, v102
	v_fmac_f32_e32 v81, v27, v103
	v_add_f32_e32 v80, v80, v81
	s_waitcnt vmcnt(0)
	v_mul_f32_e32 v81, v29, v109
	v_fmac_f32_e32 v81, v28, v108
	v_fmac_f32_e32 v81, v30, v110
	v_fmac_f32_e32 v81, v31, v111
	v_add_f32_e32 v80, v80, v81
	ds_swizzle_b32 v81, v80 offset:swizzle(SWAP,1)
	s_waitcnt lgkmcnt(0)
	v_add_f32_e32 v80, v80, v81
	ds_swizzle_b32 v81, v80 offset:swizzle(SWAP,2)
	s_waitcnt lgkmcnt(0)
	v_add_f32_e32 v80, v80, v81
	ds_swizzle_b32 v81, v80 offset:swizzle(SWAP,4)
	s_waitcnt lgkmcnt(0)
	v_add_f32_e32 v80, v80, v81
	ds_swizzle_b32 v81, v80 offset:swizzle(SWAP,8)
	s_waitcnt lgkmcnt(0)
	v_add_f32_e32 v80, v80, v81
	ds_swizzle_b32 v81, v80 offset:swizzle(SWAP,16)
	s_waitcnt lgkmcnt(0)
	v_add_f32_e32 v80, v80, v81
	s_nop 0
	v_readlane_b32 s8, v80, 0
	v_readlane_b32 s26, v80, 32
	s_and_saveexec_b64 s[24:25], s[2:3]
	s_cbranch_execz .LBB0_1076
	v_mov_b32_e32 v80, s26
	v_add_f32_e32 v80, s8, v80
	v_mul_f32_e32 v80, v114, v80
	global_store_dword v[112:113], v80, off offset:4 sc0 sc1
; __device__ __forceinline__ float rsq_(float x) { return __builtin_amdgcn_rsqf(x); }
; __device__ __forceinline__ void phase_resid(const Params& p, const float* __restrict__ gpost, float scale, const float* __restrict__ wdt) {
;     ...
; #pragma unroll
;           for (int h = 0; h < 6; ++h) {
;             const float4 w4 = *(const float4*)(wdt + h * DM + c);
;             d[h] += x4.x * w4.x + x4.y * w4.y + x4.z * w4.z + x4.w * w4.w;
;           }
;         }
;         ss = wave_sum(ss);
;         const float rsx = rsq_(ss * (1.f / DM) + EPS);
; #pragma unroll
;         for (int h = 0; h < 6; ++h) { const float v = wave_sum(d[h]); if (lane == h) L_dtbuf[row * 8 + h] = v * rsx; }
.LBB0_1076:
	s_or_b64 exec, exec, s[24:25]
	v_mul_f32_e32 v65, v17, v65
	v_fmac_f32_e32 v65, v16, v64
	v_fmac_f32_e32 v65, v18, v66
	v_fmac_f32_e32 v65, v19, v67
	v_add_f32_e32 v64, 0, v65
	v_mul_f32_e32 v65, v21, v77
	v_fmac_f32_e32 v65, v20, v76
	v_fmac_f32_e32 v65, v22, v78
	v_fmac_f32_e32 v65, v23, v79
	v_add_f32_e32 v64, v64, v65
	v_mul_f32_e32 v65, v25, v89
	v_fmac_f32_e32 v65, v24, v88
	v_fmac_f32_e32 v65, v26, v90
	v_fmac_f32_e32 v65, v27, v91
	v_add_f32_e32 v64, v64, v65
	v_mul_f32_e32 v65, v29, v105
	v_fmac_f32_e32 v65, v28, v104
	v_fmac_f32_e32 v65, v30, v106
	v_fmac_f32_e32 v65, v31, v107
	v_add_f32_e32 v64, v64, v65
	ds_swizzle_b32 v65, v64 offset:swizzle(SWAP,1)
	s_waitcnt lgkmcnt(0)
	v_add_f32_e32 v64, v64, v65
	ds_swizzle_b32 v65, v64 offset:swizzle(SWAP,2)
	s_waitcnt lgkmcnt(0)
	v_add_f32_e32 v64, v64, v65
	ds_swizzle_b32 v65, v64 offset:swizzle(SWAP,4)
	s_waitcnt lgkmcnt(0)
	v_add_f32_e32 v64, v64, v65
	ds_swizzle_b32 v65, v64 offset:swizzle(SWAP,8)
	s_waitcnt lgkmcnt(0)
	v_add_f32_e32 v64, v64, v65
	ds_swizzle_b32 v65, v64 offset:swizzle(SWAP,16)
	s_waitcnt lgkmcnt(0)
	v_add_f32_e32 v64, v64, v65
	s_nop 0
	v_readlane_b32 s8, v64, 0
	v_readlane_b32 s26, v64, 32
	s_and_saveexec_b64 s[24:25], s[4:5]
	s_cbranch_execz .LBB0_1078
	v_mov_b32_e32 v64, s26
	v_add_f32_e32 v64, s8, v64
	v_mul_f32_e32 v64, v114, v64
	global_store_dword v[112:113], v64, off offset:8 sc0 sc1
.LBB0_1078:
	s_or_b64 exec, exec, s[24:25]
	v_mul_f32_e32 v53, v17, v53
	v_fmac_f32_e32 v53, v16, v52
	v_fmac_f32_e32 v53, v18, v54
	v_fmac_f32_e32 v53, v19, v55
	v_add_f32_e32 v52, 0, v53
	v_mul_f32_e32 v53, v21, v61
	v_fmac_f32_e32 v53, v20, v60
	v_fmac_f32_e32 v53, v22, v62
	v_fmac_f32_e32 v53, v23, v63
	v_add_f32_e32 v52, v52, v53
	v_mul_f32_e32 v53, v25, v73
	v_fmac_f32_e32 v53, v24, v72
	v_fmac_f32_e32 v53, v26, v74
	v_fmac_f32_e32 v53, v27, v75
	v_add_f32_e32 v52, v52, v53
	v_mul_f32_e32 v53, v29, v97
	v_fmac_f32_e32 v53, v28, v96
	v_fmac_f32_e32 v53, v30, v98
	v_fmac_f32_e32 v53, v31, v99
	v_add_f32_e32 v52, v52, v53
	ds_swizzle_b32 v53, v52 offset:swizzle(SWAP,1)
	s_waitcnt lgkmcnt(0)
	v_add_f32_e32 v52, v52, v53
	ds_swizzle_b32 v53, v52 offset:swizzle(SWAP,2)
	s_waitcnt lgkmcnt(0)
	v_add_f32_e32 v52, v52, v53
	ds_swizzle_b32 v53, v52 offset:swizzle(SWAP,4)
	s_waitcnt lgkmcnt(0)
	v_add_f32_e32 v52, v52, v53
	ds_swizzle_b32 v53, v52 offset:swizzle(SWAP,8)
	s_waitcnt lgkmcnt(0)
	v_add_f32_e32 v52, v52, v53
	ds_swizzle_b32 v53, v52 offset:swizzle(SWAP,16)
	s_waitcnt lgkmcnt(0)
	v_add_f32_e32 v52, v52, v53
	s_nop 0
	v_readlane_b32 s8, v52, 0
	v_readlane_b32 s26, v52, 32
	s_and_saveexec_b64 s[24:25], s[6:7]
	s_cbranch_execz .LBB0_1080
	v_mov_b32_e32 v52, s26
	v_add_f32_e32 v52, s8, v52
	v_mul_f32_e32 v52, v114, v52
	global_store_dword v[112:113], v52, off offset:12 sc0 sc1
.LBB0_1080:
	s_or_b64 exec, exec, s[24:25]
	v_mul_f32_e32 v41, v17, v41
	v_fmac_f32_e32 v41, v16, v40
	v_fmac_f32_e32 v41, v18, v42
	v_fmac_f32_e32 v41, v19, v43
	v_add_f32_e32 v40, 0, v41
	v_mul_f32_e32 v41, v21, v49
	v_fmac_f32_e32 v41, v20, v48
	v_fmac_f32_e32 v41, v22, v50
	v_fmac_f32_e32 v41, v23, v51
	v_add_f32_e32 v40, v40, v41
	v_mul_f32_e32 v41, v25, v57
	v_fmac_f32_e32 v41, v24, v56
	v_fmac_f32_e32 v41, v26, v58
	v_fmac_f32_e32 v41, v27, v59
	v_add_f32_e32 v40, v40, v41
	v_mul_f32_e32 v41, v29, v85
	v_fmac_f32_e32 v41, v28, v84
	v_fmac_f32_e32 v41, v30, v86
	v_fmac_f32_e32 v41, v31, v87
	v_add_f32_e32 v40, v40, v41
	ds_swizzle_b32 v41, v40 offset:swizzle(SWAP,1)
	s_waitcnt lgkmcnt(0)
	v_add_f32_e32 v40, v40, v41
	ds_swizzle_b32 v41, v40 offset:swizzle(SWAP,2)
	s_waitcnt lgkmcnt(0)
	v_add_f32_e32 v40, v40, v41
	ds_swizzle_b32 v41, v40 offset:swizzle(SWAP,4)
	s_waitcnt lgkmcnt(0)
	v_add_f32_e32 v40, v40, v41
	ds_swizzle_b32 v41, v40 offset:swizzle(SWAP,8)
	s_waitcnt lgkmcnt(0)
	v_add_f32_e32 v40, v40, v41
	ds_swizzle_b32 v41, v40 offset:swizzle(SWAP,16)
	s_waitcnt lgkmcnt(0)
	v_add_f32_e32 v40, v40, v41
	s_nop 0
	v_readlane_b32 s8, v40, 0
	v_readlane_b32 s26, v40, 32
	s_and_saveexec_b64 s[24:25], s[12:13]
	s_cbranch_execz .LBB0_1082
	v_mov_b32_e32 v40, s26
	v_add_f32_e32 v40, s8, v40
	v_mul_f32_e32 v40, v114, v40
	global_store_dword v[112:113], v40, off offset:16 sc0 sc1
.LBB0_1082:
	s_or_b64 exec, exec, s[24:25]
	v_mul_f32_e32 v17, v17, v33
	v_fmac_f32_e32 v17, v16, v32
	v_fmac_f32_e32 v17, v18, v34
	v_fmac_f32_e32 v17, v19, v35
	v_add_f32_e32 v16, 0, v17
	v_mul_f32_e32 v17, v21, v37
	v_fmac_f32_e32 v17, v20, v36
	v_fmac_f32_e32 v17, v22, v38
	v_fmac_f32_e32 v17, v23, v39
	v_add_f32_e32 v16, v16, v17
	v_mul_f32_e32 v17, v25, v45
	v_fmac_f32_e32 v17, v24, v44
	v_fmac_f32_e32 v17, v26, v46
	v_fmac_f32_e32 v17, v27, v47
	v_add_f32_e32 v16, v16, v17
	v_mul_f32_e32 v17, v29, v69
	v_fmac_f32_e32 v17, v28, v68
	v_fmac_f32_e32 v17, v30, v70
	v_fmac_f32_e32 v17, v31, v71
	v_add_f32_e32 v16, v16, v17
	ds_swizzle_b32 v17, v16 offset:swizzle(SWAP,1)
	s_waitcnt lgkmcnt(0)
	v_add_f32_e32 v16, v16, v17
	ds_swizzle_b32 v17, v16 offset:swizzle(SWAP,2)
	s_waitcnt lgkmcnt(0)
	v_add_f32_e32 v16, v16, v17
	ds_swizzle_b32 v17, v16 offset:swizzle(SWAP,4)
	s_waitcnt lgkmcnt(0)
	v_add_f32_e32 v16, v16, v17
	ds_swizzle_b32 v17, v16 offset:swizzle(SWAP,8)
	s_waitcnt lgkmcnt(0)
	v_add_f32_e32 v16, v16, v17
	ds_swizzle_b32 v17, v16 offset:swizzle(SWAP,16)
	s_waitcnt lgkmcnt(0)
	v_add_f32_e32 v16, v16, v17
	s_nop 0
	v_readlane_b32 s8, v16, 0
	v_readlane_b32 s26, v16, 32
	s_and_saveexec_b64 s[24:25], s[14:15]
	s_cbranch_execz .LBB0_1053
	v_mov_b32_e32 v16, s26
	v_add_f32_e32 v16, s8, v16
	v_mul_f32_e32 v16, v114, v16
	global_store_dword v[112:113], v16, off offset:20 sc0 sc1
	s_branch .LBB0_1053

; template <int EPI>
; __device__ __forceinline__ void gemm_phase(const Params& p, const u16* __restrict__ A, const u16* __restrict__ Bt, int K, int nN,
;                            u16* __restrict__ Cout, int ldc) {
;     ...
; #pragma unroll
;       for (int half = 0; half < 2; ++half) {
; #pragma unroll
;         for (int mm = 0; mm < 4; ++mm) {
;           const int m = half * 4 + mm;
; #pragma unroll
;           for (int j = 0; j < 4; ++j) {
;             float rs = 1.f;
;             if (EPI == EPI_WIN) rs = rsl[wr * 128 + m * 16 + fqe * 4 + j];
;             u16* d = stg + (wr * 64 + mm * 16 + fqe * 4 + j) * 256 + (fre & 7);
; #pragma unroll
;             for (int n = 0; n < 4; ++n) {
;               const int chunk = (wc * 8 + n * 2 + (fre >> 3)) ^ (fqe << 1);
;               d[chunk * 8] = f2bf(acc[m][n][j] * rs);
;             }
;           }
;           __builtin_amdgcn_sched_barrier(0);
;         }
.Lss_epi:
	v_mov_b32_e32 v66, v181
	v_mov_b32_e32 v112, v173
	v_mov_b32_e32 v64, v191
	s_waitcnt vmcnt(0)
	s_waitcnt vmcnt(0) lgkmcnt(0)
	s_barrier
	s_mov_b32 s0, 0x10000
	v_and_b32_e32 v65, 7, v64
	v_lshlrev_b32_e32 v67, 1, v65
	v_add_u32_e32 v114, v64, v196
	v_lshlrev_b32_e32 v113, 4, v66
	v_lshl_or_b32 v66, v66, 11, v67
	v_and_b32_e32 v118, -8, v114
	v_add3_u32 v66, v66, v195, s0
	v_bitop3_b32 v114, v114, v113, -8 bitop3:0x6c
	v_add_u32_e32 v119, 16, v118
	v_cvt_pk_bf16_f32 v67, v128, s0
	v_lshl_add_u32 v114, v114, 1, v66
	v_xor_b32_e32 v119, v119, v113
	v_add_u32_e32 v120, 32, v118
	ds_write_b16 v114, v67
	v_cvt_pk_bf16_f32 v67, v132, s0
	v_lshl_add_u32 v119, v119, 1, v66
	v_xor_b32_e32 v120, v120, v113
	v_add_u32_e32 v118, 48, v118
	ds_write_b16 v119, v67
	v_cvt_pk_bf16_f32 v67, v136, s0
	v_lshl_add_u32 v120, v120, 1, v66
	v_xor_b32_e32 v113, v118, v113
	ds_write_b16 v120, v67
	v_cvt_pk_bf16_f32 v67, v140, s0
	v_lshl_add_u32 v113, v113, 1, v66
	v_cvt_pk_bf16_f32 v66, v129, s0
	ds_write_b16 v113, v67
	ds_write_b16 v114, v66 offset:512
	v_cvt_pk_bf16_f32 v66, v133, s0
	ds_write_b16 v119, v66 offset:512
	v_cvt_pk_bf16_f32 v66, v137, s0
	ds_write_b16 v120, v66 offset:512
	v_cvt_pk_bf16_f32 v66, v141, s0
	ds_write_b16 v113, v66 offset:512
	v_cvt_pk_bf16_f32 v66, v130, s0
	ds_write_b16 v114, v66 offset:1024
	v_cvt_pk_bf16_f32 v66, v134, s0
	ds_write_b16 v119, v66 offset:1024
	v_cvt_pk_bf16_f32 v66, v138, s0
	ds_write_b16 v120, v66 offset:1024
	v_cvt_pk_bf16_f32 v66, v142, s0
	ds_write_b16 v113, v66 offset:1024
	v_cvt_pk_bf16_f32 v66, v131, s0
	v_and_b32_e32 v64, 31, v112
	v_lshrrev_b32_e32 v65, 6, v112
	ds_write_b16 v114, v66 offset:1536
	v_cvt_pk_bf16_f32 v66, v135, s0
	v_bitop3_b32 v65, v65, v64, 6 bitop3:0x6c
	ds_write_b16 v119, v66 offset:1536
	v_cvt_pk_bf16_f32 v66, v139, s0
	v_lshl_or_b32 v115, v65, 4, v188
	v_lshl_or_b32 v64, v64, 3, s28
	v_mov_b32_e32 v65, v172
	v_ashrrev_i32_e32 v116, 5, v112
	ds_write_b16 v120, v66 offset:1536
	v_cvt_pk_bf16_f32 v66, v143, s0
	v_lshl_add_u64 v[64:65], v[64:65], 1, s[2:3]
	v_lshl_add_u32 v117, v116, 9, v115
	ds_write_b16 v113, v66 offset:1536
	v_cvt_pk_bf16_f32 v66, v108, s0
	ds_write_b16 v114, v66 offset:8192
	v_cvt_pk_bf16_f32 v66, v104, s0
	ds_write_b16 v119, v66 offset:8192
	v_cvt_pk_bf16_f32 v66, v100, s0
	ds_write_b16 v120, v66 offset:8192
	v_cvt_pk_bf16_f32 v66, v96, s0
	ds_write_b16 v113, v66 offset:8192
	v_cvt_pk_bf16_f32 v66, v109, s0
	ds_write_b16 v114, v66 offset:8704
	v_cvt_pk_bf16_f32 v66, v105, s0
	ds_write_b16 v119, v66 offset:8704
	v_cvt_pk_bf16_f32 v66, v101, s0
	ds_write_b16 v120, v66 offset:8704
	v_cvt_pk_bf16_f32 v66, v97, s0
	ds_write_b16 v113, v66 offset:8704
	v_cvt_pk_bf16_f32 v66, v110, s0
	ds_write_b16 v114, v66 offset:9216
	v_cvt_pk_bf16_f32 v66, v106, s0
	ds_write_b16 v119, v66 offset:9216
	v_cvt_pk_bf16_f32 v66, v102, s0
	ds_write_b16 v120, v66 offset:9216
	v_cvt_pk_bf16_f32 v66, v98, s0
	ds_write_b16 v113, v66 offset:9216
	v_cvt_pk_bf16_f32 v66, v111, s0
	ds_write_b16 v114, v66 offset:9728
	v_cvt_pk_bf16_f32 v66, v107, s0
	ds_write_b16 v119, v66 offset:9728
	v_cvt_pk_bf16_f32 v66, v103, s0
	ds_write_b16 v120, v66 offset:9728
	v_cvt_pk_bf16_f32 v66, v99, s0
	ds_write_b16 v113, v66 offset:9728
	v_cvt_pk_bf16_f32 v66, v92, s0
	ds_write_b16 v114, v66 offset:16384
	v_cvt_pk_bf16_f32 v66, v88, s0
	ds_write_b16 v119, v66 offset:16384
	v_cvt_pk_bf16_f32 v66, v84, s0
	ds_write_b16 v120, v66 offset:16384
	v_cvt_pk_bf16_f32 v66, v80, s0
	ds_write_b16 v113, v66 offset:16384
	v_cvt_pk_bf16_f32 v66, v93, s0
	ds_write_b16 v114, v66 offset:16896
	v_cvt_pk_bf16_f32 v66, v89, s0
	ds_write_b16 v119, v66 offset:16896
	v_cvt_pk_bf16_f32 v66, v85, s0
	ds_write_b16 v120, v66 offset:16896
	v_cvt_pk_bf16_f32 v66, v81, s0
	ds_write_b16 v113, v66 offset:16896
	v_cvt_pk_bf16_f32 v66, v94, s0
	ds_write_b16 v114, v66 offset:17408
	v_cvt_pk_bf16_f32 v66, v90, s0
	ds_write_b16 v119, v66 offset:17408
	v_cvt_pk_bf16_f32 v66, v86, s0
	ds_write_b16 v120, v66 offset:17408
	v_cvt_pk_bf16_f32 v66, v82, s0
	ds_write_b16 v113, v66 offset:17408
	v_cvt_pk_bf16_f32 v66, v95, s0
	ds_write_b16 v114, v66 offset:17920
	v_cvt_pk_bf16_f32 v66, v91, s0
	ds_write_b16 v119, v66 offset:17920
	v_cvt_pk_bf16_f32 v66, v87, s0
	ds_write_b16 v120, v66 offset:17920
	v_cvt_pk_bf16_f32 v66, v83, s0
	ds_write_b16 v113, v66 offset:17920
	v_cvt_pk_bf16_f32 v66, v76, s0
	ds_write_b16 v114, v66 offset:24576
	v_cvt_pk_bf16_f32 v66, v72, s0
	ds_write_b16 v119, v66 offset:24576
	v_cvt_pk_bf16_f32 v66, v68, s0
	ds_write_b16 v120, v66 offset:24576
	v_cvt_pk_bf16_f32 v66, v148, s0
	ds_write_b16 v113, v66 offset:24576
	v_cvt_pk_bf16_f32 v66, v77, s0
	ds_write_b16 v114, v66 offset:25088
	v_cvt_pk_bf16_f32 v66, v73, s0
	ds_write_b16 v119, v66 offset:25088
	v_cvt_pk_bf16_f32 v66, v69, s0
	ds_write_b16 v120, v66 offset:25088
	v_cvt_pk_bf16_f32 v66, v149, s0
	ds_write_b16 v113, v66 offset:25088
	v_cvt_pk_bf16_f32 v66, v78, s0
	ds_write_b16 v114, v66 offset:25600
	v_cvt_pk_bf16_f32 v66, v74, s0
	ds_write_b16 v119, v66 offset:25600
	v_cvt_pk_bf16_f32 v66, v70, s0
	ds_write_b16 v120, v66 offset:25600
	v_cvt_pk_bf16_f32 v66, v150, s0
	ds_write_b16 v113, v66 offset:25600
	v_cvt_pk_bf16_f32 v66, v79, s0
	ds_write_b16 v114, v66 offset:26112
	v_cvt_pk_bf16_f32 v66, v75, s0
	ds_write_b16 v119, v66 offset:26112
	v_cvt_pk_bf16_f32 v66, v71, s0
	ds_write_b16 v120, v66 offset:26112
	v_cvt_pk_bf16_f32 v66, v151, s0
	ds_write_b16 v113, v66 offset:26112
	v_lshrrev_b32_e32 v70, 4, v112
	s_waitcnt lgkmcnt(0)
	s_barrier
; template <int EPI>
; __device__ __forceinline__ void gemm_phase(const Params& p, const u16* __restrict__ A, const u16* __restrict__ Bt, int K, int nN,
;                            u16* __restrict__ Cout, int ldc) {
;     ...
;         __syncthreads();
; #pragma unroll
;         for (int it = 0; it < 8; ++it) {
;           const int id = it * 512 + tide, r = id >> 5, ck = id & 31;
;           const uint4 v = *(const uint4*)(stg + r * 256 + ((ck ^ (((r >> 2) & 3) << 1)) * 8));
;           const int grow = brow + (r >> 6) * 128 + half * 64 + (r & 63);
;           if (EPI == EPI_WIN) { typedef __attribute__((ext_vector_type(4))) unsigned u32x4_; const u32x4_ t_ = {v.x, v.y, v.z, v.w};
;             __builtin_nontemporal_store(t_, (u32x4_*)(Cout + (unsigned)grow * (unsigned)ldc + (unsigned)(bcol + ck * 8))); }
;           else *(uint4*)(Cout + (unsigned)grow * (unsigned)ldc + (unsigned)(bcol + ck * 8)) = v;
;         }
;         asm volatile("s_waitcnt lgkmcnt(0)" ::: "memory"); __builtin_amdgcn_s_barrier();
	ds_read_b128 v[66:69], v117
	v_and_b32_e32 v72, 0x3fff80, v70
	v_add_u32_e32 v70, s27, v72
	v_and_b32_e32 v73, 63, v116
	v_or_b32_e32 v70, v70, v73
	v_lshlrev_b32_e32 v70, 10, v70
	v_mov_b32_e32 v71, v172
	v_lshl_add_u64 v[70:71], v[70:71], 1, v[64:65]
	s_waitcnt lgkmcnt(0)
	global_store_dwordx4 v[70:71], v[66:69], off sc0 sc1
	v_add_u32_e32 v70, 0x200, v112
	v_ashrrev_i32_e32 v71, 5, v70
	v_lshl_add_u32 v74, v71, 9, v115
	v_lshrrev_b32_e32 v70, 4, v70
	ds_read_b128 v[66:69], v74
	v_and_b32_e32 v75, 0x3fff80, v70
	v_add_u32_e32 v70, s27, v75
	v_and_b32_e32 v76, 63, v71
	v_or_b32_e32 v70, v70, v76
	v_lshlrev_b32_e32 v70, 10, v70
	v_mov_b32_e32 v71, v172
	v_lshl_add_u64 v[70:71], v[70:71], 1, v[64:65]
	s_waitcnt lgkmcnt(0)
	global_store_dwordx4 v[70:71], v[66:69], off sc0 sc1
	v_add_u32_e32 v70, 0x400, v112
	v_ashrrev_i32_e32 v71, 5, v70
	v_lshl_add_u32 v77, v71, 9, v115
	v_lshrrev_b32_e32 v70, 4, v70
	ds_read_b128 v[66:69], v77
	v_and_b32_e32 v78, 0x3fff80, v70
	v_add_u32_e32 v70, s27, v78
	v_and_b32_e32 v79, 63, v71
	v_or_b32_e32 v70, v70, v79
	v_lshlrev_b32_e32 v70, 10, v70
	v_mov_b32_e32 v71, v172
	v_lshl_add_u64 v[70:71], v[70:71], 1, v[64:65]
	s_waitcnt lgkmcnt(0)
	global_store_dwordx4 v[70:71], v[66:69], off sc0 sc1
	v_add_u32_e32 v70, 0x600, v112
	v_ashrrev_i32_e32 v71, 5, v70
	v_lshl_add_u32 v80, v71, 9, v115
	v_lshrrev_b32_e32 v70, 4, v70
	ds_read_b128 v[66:69], v80
	v_and_b32_e32 v81, 0x3fff80, v70
	v_add_u32_e32 v70, s27, v81
	v_and_b32_e32 v82, 63, v71
	v_or_b32_e32 v70, v70, v82
	v_lshlrev_b32_e32 v70, 10, v70
	v_mov_b32_e32 v71, v172
	v_lshl_add_u64 v[70:71], v[70:71], 1, v[64:65]
	s_waitcnt lgkmcnt(0)
	global_store_dwordx4 v[70:71], v[66:69], off sc0 sc1
	v_add_u32_e32 v70, 0x800, v112
	v_ashrrev_i32_e32 v71, 5, v70
	v_lshl_add_u32 v83, v71, 9, v115
	v_lshrrev_b32_e32 v70, 4, v70
	ds_read_b128 v[66:69], v83
	v_and_b32_e32 v84, 0x3fff80, v70
	v_add_u32_e32 v70, s27, v84
	v_and_b32_e32 v85, 63, v71
	v_or_b32_e32 v70, v70, v85
	v_lshlrev_b32_e32 v70, 10, v70
	v_mov_b32_e32 v71, v172
	v_lshl_add_u64 v[70:71], v[70:71], 1, v[64:65]
	s_waitcnt lgkmcnt(0)
	global_store_dwordx4 v[70:71], v[66:69], off sc0 sc1
	v_add_u32_e32 v70, 0xa00, v112
	v_ashrrev_i32_e32 v71, 5, v70
	v_lshl_add_u32 v86, v71, 9, v115
	v_lshrrev_b32_e32 v70, 4, v70
	ds_read_b128 v[66:69], v86
	v_and_b32_e32 v87, 0x3fff80, v70
	v_add_u32_e32 v70, s27, v87
	v_and_b32_e32 v88, 63, v71
	v_or_b32_e32 v70, v70, v88
	v_lshlrev_b32_e32 v70, 10, v70
	v_mov_b32_e32 v71, v172
	v_lshl_add_u64 v[70:71], v[70:71], 1, v[64:65]
	s_waitcnt lgkmcnt(0)
	global_store_dwordx4 v[70:71], v[66:69], off sc0 sc1
	v_add_u32_e32 v70, 0xc00, v112
	v_ashrrev_i32_e32 v71, 5, v70
	v_lshl_add_u32 v89, v71, 9, v115
	v_lshrrev_b32_e32 v70, 4, v70
	ds_read_b128 v[66:69], v89
	v_and_b32_e32 v90, 0x3fff80, v70
	v_add_u32_e32 v70, s27, v90
	v_and_b32_e32 v91, 63, v71
	v_or_b32_e32 v70, v70, v91
	v_lshlrev_b32_e32 v70, 10, v70
	v_mov_b32_e32 v71, v172
	v_lshl_add_u64 v[70:71], v[70:71], 1, v[64:65]
	s_waitcnt lgkmcnt(0)
	global_store_dwordx4 v[70:71], v[66:69], off sc0 sc1
	v_add_u32_e32 v70, 0xe00, v112
	v_ashrrev_i32_e32 v71, 5, v70
	v_lshl_add_u32 v92, v71, 9, v115
	v_lshrrev_b32_e32 v70, 4, v70
	ds_read_b128 v[66:69], v92
	v_and_b32_e32 v93, 0x3fff80, v70
	v_add_u32_e32 v70, s27, v93
	v_and_b32_e32 v94, 63, v71
	v_or_b32_e32 v70, v70, v94
	v_lshlrev_b32_e32 v70, 10, v70
	v_mov_b32_e32 v71, v172
	v_lshl_add_u64 v[70:71], v[70:71], 1, v[64:65]
	s_waitcnt lgkmcnt(0)
	global_store_dwordx4 v[70:71], v[66:69], off sc0 sc1
	v_cvt_pk_bf16_f32 v48, v48, s0
	s_waitcnt lgkmcnt(0)
	s_barrier
; template <int EPI>
; __device__ __forceinline__ void gemm_phase(const Params& p, const u16* __restrict__ A, const u16* __restrict__ Bt, int K, int nN,
;                            u16* __restrict__ Cout, int ldc) {
;     ...
; #pragma unroll
;       for (int half = 0; half < 2; ++half) {
; #pragma unroll
;         for (int mm = 0; mm < 4; ++mm) {
;           const int m = half * 4 + mm;
; #pragma unroll
;           for (int j = 0; j < 4; ++j) {
;             float rs = 1.f;
;             if (EPI == EPI_WIN) rs = rsl[wr * 128 + m * 16 + fqe * 4 + j];
;             u16* d = stg + (wr * 64 + mm * 16 + fqe * 4 + j) * 256 + (fre & 7);
; #pragma unroll
;             for (int n = 0; n < 4; ++n) {
;               const int chunk = (wc * 8 + n * 2 + (fre >> 3)) ^ (fqe << 1);
;               d[chunk * 8] = f2bf(acc[m][n][j] * rs);
;             }
;           }
;           __builtin_amdgcn_sched_barrier(0);
;         }
;         __syncthreads();
; #pragma unroll
;         for (int it = 0; it < 8; ++it) {
;           const int id = it * 512 + tide, r = id >> 5, ck = id & 31;
;           const uint4 v = *(const uint4*)(stg + r * 256 + ((ck ^ (((r >> 2) & 3) << 1)) * 8));
;           const int grow = brow + (r >> 6) * 128 + half * 64 + (r & 63);
;           if (EPI == EPI_WIN) { typedef __attribute__((ext_vector_type(4))) unsigned u32x4_; const u32x4_ t_ = {v.x, v.y, v.z, v.w};
;             __builtin_nontemporal_store(t_, (u32x4_*)(Cout + (unsigned)grow * (unsigned)ldc + (unsigned)(bcol + ck * 8))); }
;           else *(uint4*)(Cout + (unsigned)grow * (unsigned)ldc + (unsigned)(bcol + ck * 8)) = v;
;         }
;         asm volatile("s_waitcnt lgkmcnt(0)" ::: "memory"); __builtin_amdgcn_s_barrier();
	v_cvt_pk_bf16_f32 v56, v56, s0
	v_cvt_pk_bf16_f32 v52, v52, s0
	ds_write_b16 v113, v48
	v_cvt_pk_bf16_f32 v48, v61, s0
	v_cvt_pk_bf16_f32 v60, v60, s0
	ds_write_b16 v119, v56
	ds_write_b16 v120, v52
	ds_write_b16 v114, v48 offset:512
	v_cvt_pk_bf16_f32 v48, v57, s0
	ds_write_b16 v114, v60
	ds_write_b16 v119, v48 offset:512
	v_cvt_pk_bf16_f32 v48, v53, s0
	ds_write_b16 v120, v48 offset:512
	v_cvt_pk_bf16_f32 v48, v49, s0
	ds_write_b16 v113, v48 offset:512
	v_cvt_pk_bf16_f32 v48, v62, s0
	ds_write_b16 v114, v48 offset:1024
	v_cvt_pk_bf16_f32 v48, v58, s0
	ds_write_b16 v119, v48 offset:1024
	v_cvt_pk_bf16_f32 v48, v54, s0
	ds_write_b16 v120, v48 offset:1024
	v_cvt_pk_bf16_f32 v48, v50, s0
	ds_write_b16 v113, v48 offset:1024
	v_cvt_pk_bf16_f32 v48, v63, s0
	ds_write_b16 v114, v48 offset:1536
	v_cvt_pk_bf16_f32 v48, v59, s0
	ds_write_b16 v119, v48 offset:1536
	v_cvt_pk_bf16_f32 v48, v55, s0
	ds_write_b16 v120, v48 offset:1536
	v_cvt_pk_bf16_f32 v48, v51, s0
	ds_write_b16 v113, v48 offset:1536
	v_cvt_pk_bf16_f32 v32, v32, s0
	v_cvt_pk_bf16_f32 v40, v40, s0
	v_cvt_pk_bf16_f32 v36, v36, s0
	ds_write_b16 v113, v32 offset:8192
	v_cvt_pk_bf16_f32 v32, v45, s0
	v_cvt_pk_bf16_f32 v44, v44, s0
	ds_write_b16 v119, v40 offset:8192
	ds_write_b16 v120, v36 offset:8192
	ds_write_b16 v114, v32 offset:8704
	v_cvt_pk_bf16_f32 v32, v41, s0
	ds_write_b16 v114, v44 offset:8192
	ds_write_b16 v119, v32 offset:8704
	v_cvt_pk_bf16_f32 v32, v37, s0
	ds_write_b16 v120, v32 offset:8704
	v_cvt_pk_bf16_f32 v32, v33, s0
	ds_write_b16 v113, v32 offset:8704
	v_cvt_pk_bf16_f32 v32, v46, s0
	ds_write_b16 v114, v32 offset:9216
	v_cvt_pk_bf16_f32 v32, v42, s0
	ds_write_b16 v119, v32 offset:9216
	v_cvt_pk_bf16_f32 v32, v38, s0
	ds_write_b16 v120, v32 offset:9216
	v_cvt_pk_bf16_f32 v32, v34, s0
	ds_write_b16 v113, v32 offset:9216
	v_cvt_pk_bf16_f32 v32, v47, s0
	ds_write_b16 v114, v32 offset:9728
	v_cvt_pk_bf16_f32 v32, v43, s0
	ds_write_b16 v119, v32 offset:9728
	v_cvt_pk_bf16_f32 v32, v39, s0
	ds_write_b16 v120, v32 offset:9728
	v_cvt_pk_bf16_f32 v32, v35, s0
	ds_write_b16 v113, v32 offset:9728
	v_cvt_pk_bf16_f32 v16, v16, s0
	v_cvt_pk_bf16_f32 v24, v24, s0
	v_cvt_pk_bf16_f32 v20, v20, s0
	ds_write_b16 v113, v16 offset:16384
	v_cvt_pk_bf16_f32 v16, v29, s0
	v_cvt_pk_bf16_f32 v28, v28, s0
	ds_write_b16 v119, v24 offset:16384
	ds_write_b16 v120, v20 offset:16384
	ds_write_b16 v114, v16 offset:16896
	v_cvt_pk_bf16_f32 v16, v25, s0
	ds_write_b16 v114, v28 offset:16384
	ds_write_b16 v119, v16 offset:16896
	v_cvt_pk_bf16_f32 v16, v21, s0
	ds_write_b16 v120, v16 offset:16896
	v_cvt_pk_bf16_f32 v16, v17, s0
	ds_write_b16 v113, v16 offset:16896
	v_cvt_pk_bf16_f32 v16, v30, s0
	ds_write_b16 v114, v16 offset:17408
	v_cvt_pk_bf16_f32 v16, v26, s0
	ds_write_b16 v119, v16 offset:17408
	v_cvt_pk_bf16_f32 v16, v22, s0
	ds_write_b16 v120, v16 offset:17408
	v_cvt_pk_bf16_f32 v16, v18, s0
	ds_write_b16 v113, v16 offset:17408
	v_cvt_pk_bf16_f32 v16, v31, s0
	ds_write_b16 v114, v16 offset:17920
	v_cvt_pk_bf16_f32 v16, v27, s0
	ds_write_b16 v119, v16 offset:17920
	v_cvt_pk_bf16_f32 v16, v23, s0
	ds_write_b16 v120, v16 offset:17920
	v_cvt_pk_bf16_f32 v16, v19, s0
	ds_write_b16 v113, v16 offset:17920
	v_cvt_pk_bf16_f32 v0, v0, s0
	v_cvt_pk_bf16_f32 v8, v8, s0
	v_cvt_pk_bf16_f32 v4, v4, s0
	ds_write_b16 v113, v0 offset:24576
	v_cvt_pk_bf16_f32 v0, v13, s0
	v_cvt_pk_bf16_f32 v12, v12, s0
	ds_write_b16 v119, v8 offset:24576
	ds_write_b16 v120, v4 offset:24576
	ds_write_b16 v114, v0 offset:25088
	v_cvt_pk_bf16_f32 v0, v9, s0
	ds_write_b16 v114, v12 offset:24576
	ds_write_b16 v119, v0 offset:25088
	v_cvt_pk_bf16_f32 v0, v5, s0
	ds_write_b16 v120, v0 offset:25088
	v_cvt_pk_bf16_f32 v0, v1, s0
	ds_write_b16 v113, v0 offset:25088
	v_cvt_pk_bf16_f32 v0, v14, s0
	ds_write_b16 v114, v0 offset:25600
	v_cvt_pk_bf16_f32 v0, v10, s0
	ds_write_b16 v119, v0 offset:25600
	v_cvt_pk_bf16_f32 v0, v6, s0
	ds_write_b16 v120, v0 offset:25600
	v_cvt_pk_bf16_f32 v0, v2, s0
	ds_write_b16 v113, v0 offset:25600
	v_cvt_pk_bf16_f32 v0, v15, s0
	ds_write_b16 v114, v0 offset:26112
	v_cvt_pk_bf16_f32 v0, v11, s0
	ds_write_b16 v119, v0 offset:26112
	v_cvt_pk_bf16_f32 v0, v7, s0
	ds_write_b16 v120, v0 offset:26112
	v_cvt_pk_bf16_f32 v0, v3, s0
	ds_write_b16 v113, v0 offset:26112
	s_waitcnt lgkmcnt(0)
	s_barrier
	s_or_b32 s0, s27, 64
	ds_read_b128 v[0:3], v117
	v_add_u32_e32 v4, s0, v72
	v_or_b32_e32 v4, v4, v73
	v_lshlrev_b32_e32 v4, 10, v4
	v_mov_b32_e32 v5, v172
	v_lshl_add_u64 v[4:5], v[4:5], 1, v[64:65]
	s_waitcnt lgkmcnt(0)
	global_store_dwordx4 v[4:5], v[0:3], off sc0 sc1
	ds_read_b128 v[0:3], v74
	v_add_u32_e32 v4, s0, v75
	v_or_b32_e32 v4, v4, v76
	v_lshlrev_b32_e32 v4, 10, v4
	v_mov_b32_e32 v5, v172
	v_lshl_add_u64 v[4:5], v[4:5], 1, v[64:65]
	s_waitcnt lgkmcnt(0)
	global_store_dwordx4 v[4:5], v[0:3], off sc0 sc1
	ds_read_b128 v[0:3], v77
	v_add_u32_e32 v4, s0, v78
	v_or_b32_e32 v4, v4, v79
	v_lshlrev_b32_e32 v4, 10, v4
	v_mov_b32_e32 v5, v172
	v_lshl_add_u64 v[4:5], v[4:5], 1, v[64:65]
	s_waitcnt lgkmcnt(0)
	global_store_dwordx4 v[4:5], v[0:3], off sc0 sc1
	ds_read_b128 v[0:3], v80
	v_add_u32_e32 v4, s0, v81
	v_or_b32_e32 v4, v4, v82
	v_lshlrev_b32_e32 v4, 10, v4
	v_mov_b32_e32 v5, v172
	v_lshl_add_u64 v[4:5], v[4:5], 1, v[64:65]
	s_waitcnt lgkmcnt(0)
	global_store_dwordx4 v[4:5], v[0:3], off sc0 sc1
	ds_read_b128 v[0:3], v83
	v_add_u32_e32 v4, s0, v84
	v_or_b32_e32 v4, v4, v85
	v_lshlrev_b32_e32 v4, 10, v4
	v_mov_b32_e32 v5, v172
	v_lshl_add_u64 v[4:5], v[4:5], 1, v[64:65]
	s_waitcnt lgkmcnt(0)
	global_store_dwordx4 v[4:5], v[0:3], off sc0 sc1
	ds_read_b128 v[0:3], v86
	v_add_u32_e32 v4, s0, v87
	v_or_b32_e32 v4, v4, v88
	v_lshlrev_b32_e32 v4, 10, v4
	v_mov_b32_e32 v5, v172
	v_lshl_add_u64 v[4:5], v[4:5], 1, v[64:65]
	s_waitcnt lgkmcnt(0)
	global_store_dwordx4 v[4:5], v[0:3], off sc0 sc1
	ds_read_b128 v[0:3], v89
	v_add_u32_e32 v4, s0, v90
	v_or_b32_e32 v4, v4, v91
	v_lshlrev_b32_e32 v4, 10, v4
	v_mov_b32_e32 v5, v172
	v_lshl_add_u64 v[4:5], v[4:5], 1, v[64:65]
	s_waitcnt lgkmcnt(0)
	global_store_dwordx4 v[4:5], v[0:3], off sc0 sc1
	ds_read_b128 v[0:3], v92
	v_add_u32_e32 v4, s0, v93
	v_or_b32_e32 v4, v4, v94
	v_lshlrev_b32_e32 v4, 10, v4
	v_mov_b32_e32 v5, v172
	v_lshl_add_u64 v[4:5], v[4:5], 1, v[64:65]
	s_waitcnt lgkmcnt(0)
	global_store_dwordx4 v[4:5], v[0:3], off sc0 sc1
	s_waitcnt lgkmcnt(0)
	s_mov_b64 s[0:1], -1
	s_and_b64 vcc, exec, s[4:5]
	s_barrier
	s_cbranch_vccnz .LBB0_1122

; __device__ __forceinline__ float silu_(float x) { return x * rcp_(1.f + __expf(-x)); }
; template <int EPI>
; __device__ __forceinline__ void gemm_phase(const Params& p, const u16* __restrict__ A, const u16* __restrict__ Bt, int K, int nN,
;                            u16* __restrict__ Cout, int ldc) {
;     ...
;     if (EPI == EPI_GU) {
; #pragma unroll
;       for (int m = 0; m < 8; ++m) {
; #pragma unroll
;         for (int j = 0; j < 4; ++j) {
;           const float rs = rsl[wr * 128 + m * 16 + fqe * 4 + j];
;           u16* d = stg + (wr * 128 + m * 16 + fqe * 4 + j) * 128 + (fre & 7);
; #pragma unroll
;           for (int n2 = 0; n2 < 2; ++n2) {
;             const float g = acc[m][2 * n2][j] * rs, u = acc[m][2 * n2 + 1][j] * rs;
;             const int chunk = (wc * 4 + n2 * 2 + (fre >> 3)) ^ fqe;
;             d[chunk * 8] = f2bf(silu_(g) * u);
;           }
;         }
;         __builtin_amdgcn_sched_barrier(0);
;       }
.LBB0_1126:
	v_lshl_add_u32 v222, v192, 2, v196
	v_lshl_add_u32 v223, v222, 2, v187
	ds_read_b128 v[128:131], v223 offset:0
	ds_read_b128 v[132:135], v223 offset:64
	ds_read_b128 v[136:139], v223 offset:128
	ds_read_b128 v[140:143], v223 offset:192
	ds_read_b128 v[144:147], v223 offset:256
	ds_read_b128 v[148:151], v223 offset:320
	ds_read_b128 v[152:155], v223 offset:384
	ds_read_b128 v[156:159], v223 offset:448
	v_and_b32_e32 v224, 7, v174
	v_lshrrev_b32_e32 v225, 3, v174
	v_add_u32_e32 v225, v225, v197
	v_lshlrev_b32_e32 v224, 1, v224
	v_lshl_or_b32 v224, v222, 8, v224
	v_xor_b32_e32 v226, v225, v192
	v_add_u32_e32 v227, 2, v225
	v_xor_b32_e32 v227, v227, v192
	v_lshl_add_u32 v160, v226, 4, v224
	v_lshl_add_u32 v161, v227, 4, v224
	v_add_u32_e32 v160, 0x10000, v160
	v_add_u32_e32 v161, 0x10000, v161
	s_waitcnt lgkmcnt(0)
	v_mov_b32_e32 v228, 0xbfb8aa3b
	v_mov_b32_e32 v229, 0xbfb8aa3b
	v_mov_b32_e32 v230, 1.0
	v_mov_b32_e32 v231, 1.0
	v_pk_mul_f32 v[162:163], v[124:125], v[128:129]
	v_pk_mul_f32 v[164:165], v[126:127], v[130:131]
	v_pk_mul_f32 v[166:167], v[116:117], v[128:129]
	v_pk_mul_f32 v[168:169], v[118:119], v[130:131]
	v_pk_mul_f32 v[214:215], v[162:163], v[228:229]
	v_pk_mul_f32 v[216:217], v[164:165], v[228:229]
	v_pk_mul_f32 v[218:219], v[166:167], v[228:229]
	v_pk_mul_f32 v[220:221], v[168:169], v[228:229]
	v_exp_f32_e32 v214, v214
	v_exp_f32_e32 v215, v215
	v_exp_f32_e32 v216, v216
	v_exp_f32_e32 v217, v217
	v_exp_f32_e32 v218, v218
	v_exp_f32_e32 v219, v219
	v_exp_f32_e32 v220, v220
	v_exp_f32_e32 v221, v221
	v_pk_mul_f32 v[206:207], v[120:121], v[128:129]
	v_pk_mul_f32 v[208:209], v[122:123], v[130:131]
	v_pk_mul_f32 v[210:211], v[112:113], v[128:129]
	v_pk_mul_f32 v[212:213], v[114:115], v[130:131]
	v_pk_add_f32 v[214:215], v[214:215], v[230:231]
	v_pk_add_f32 v[216:217], v[216:217], v[230:231]
	v_pk_add_f32 v[218:219], v[218:219], v[230:231]
	v_pk_add_f32 v[220:221], v[220:221], v[230:231]
	v_rcp_f32_e32 v214, v214
	v_rcp_f32_e32 v215, v215
	v_rcp_f32_e32 v216, v216
	v_rcp_f32_e32 v217, v217
	v_rcp_f32_e32 v218, v218
	v_rcp_f32_e32 v219, v219
	v_rcp_f32_e32 v220, v220
	v_rcp_f32_e32 v221, v221
	v_pk_mul_f32 v[162:163], v[162:163], v[214:215]
	v_pk_mul_f32 v[164:165], v[164:165], v[216:217]
	v_pk_mul_f32 v[166:167], v[166:167], v[218:219]
	v_pk_mul_f32 v[168:169], v[168:169], v[220:221]
	v_pk_mul_f32 v[206:207], v[206:207], v[162:163]
	v_pk_mul_f32 v[208:209], v[208:209], v[164:165]
	v_pk_mul_f32 v[210:211], v[210:211], v[166:167]
	v_pk_mul_f32 v[212:213], v[212:213], v[168:169]
	v_cvt_pk_bf16_f32 v206, v206, v207
	v_cvt_pk_bf16_f32 v208, v208, v209
	v_cvt_pk_bf16_f32 v210, v210, v211
	v_cvt_pk_bf16_f32 v212, v212, v213
	ds_write_b16 v160, v206 offset:0
	ds_write_b16_d16_hi v160, v206 offset:256
	ds_write_b16 v160, v208 offset:512
	ds_write_b16_d16_hi v160, v208 offset:768
	ds_write_b16 v161, v210 offset:0
	ds_write_b16_d16_hi v161, v210 offset:256
	ds_write_b16 v161, v212 offset:512
	ds_write_b16_d16_hi v161, v212 offset:768
	v_pk_mul_f32 v[162:163], v[108:109], v[132:133]
	v_pk_mul_f32 v[164:165], v[110:111], v[134:135]
	v_pk_mul_f32 v[166:167], v[100:101], v[132:133]
	v_pk_mul_f32 v[168:169], v[102:103], v[134:135]
	v_pk_mul_f32 v[214:215], v[162:163], v[228:229]
	v_pk_mul_f32 v[216:217], v[164:165], v[228:229]
	v_pk_mul_f32 v[218:219], v[166:167], v[228:229]
	v_pk_mul_f32 v[220:221], v[168:169], v[228:229]
	v_exp_f32_e32 v214, v214
	v_exp_f32_e32 v215, v215
	v_exp_f32_e32 v216, v216
	v_exp_f32_e32 v217, v217
	v_exp_f32_e32 v218, v218
	v_exp_f32_e32 v219, v219
	v_exp_f32_e32 v220, v220
	v_exp_f32_e32 v221, v221
	v_pk_mul_f32 v[206:207], v[104:105], v[132:133]
	v_pk_mul_f32 v[208:209], v[106:107], v[134:135]
	v_pk_mul_f32 v[210:211], v[96:97], v[132:133]
	v_pk_mul_f32 v[212:213], v[98:99], v[134:135]
	v_pk_add_f32 v[214:215], v[214:215], v[230:231]
	v_pk_add_f32 v[216:217], v[216:217], v[230:231]
	v_pk_add_f32 v[218:219], v[218:219], v[230:231]
	v_pk_add_f32 v[220:221], v[220:221], v[230:231]
	v_rcp_f32_e32 v214, v214
	v_rcp_f32_e32 v215, v215
	v_rcp_f32_e32 v216, v216
	v_rcp_f32_e32 v217, v217
	v_rcp_f32_e32 v218, v218
	v_rcp_f32_e32 v219, v219
	v_rcp_f32_e32 v220, v220
	v_rcp_f32_e32 v221, v221
	v_pk_mul_f32 v[162:163], v[162:163], v[214:215]
	v_pk_mul_f32 v[164:165], v[164:165], v[216:217]
	v_pk_mul_f32 v[166:167], v[166:167], v[218:219]
	v_pk_mul_f32 v[168:169], v[168:169], v[220:221]
	v_pk_mul_f32 v[206:207], v[206:207], v[162:163]
	v_pk_mul_f32 v[208:209], v[208:209], v[164:165]
	v_pk_mul_f32 v[210:211], v[210:211], v[166:167]
	v_pk_mul_f32 v[212:213], v[212:213], v[168:169]
	v_cvt_pk_bf16_f32 v206, v206, v207
	v_cvt_pk_bf16_f32 v208, v208, v209
	v_cvt_pk_bf16_f32 v210, v210, v211
	v_cvt_pk_bf16_f32 v212, v212, v213
	ds_write_b16 v160, v206 offset:4096
	ds_write_b16_d16_hi v160, v206 offset:4352
	ds_write_b16 v160, v208 offset:4608
	ds_write_b16_d16_hi v160, v208 offset:4864
	ds_write_b16 v161, v210 offset:4096
	ds_write_b16_d16_hi v161, v210 offset:4352
	ds_write_b16 v161, v212 offset:4608
	ds_write_b16_d16_hi v161, v212 offset:4864
	v_pk_mul_f32 v[162:163], v[92:93], v[136:137]
	v_pk_mul_f32 v[164:165], v[94:95], v[138:139]
	v_pk_mul_f32 v[166:167], v[84:85], v[136:137]
	v_pk_mul_f32 v[168:169], v[86:87], v[138:139]
	v_pk_mul_f32 v[214:215], v[162:163], v[228:229]
	v_pk_mul_f32 v[216:217], v[164:165], v[228:229]
	v_pk_mul_f32 v[218:219], v[166:167], v[228:229]
	v_pk_mul_f32 v[220:221], v[168:169], v[228:229]
	v_exp_f32_e32 v214, v214
	v_exp_f32_e32 v215, v215
	v_exp_f32_e32 v216, v216
	v_exp_f32_e32 v217, v217
	v_exp_f32_e32 v218, v218
	v_exp_f32_e32 v219, v219
	v_exp_f32_e32 v220, v220
	v_exp_f32_e32 v221, v221
; __device__ __forceinline__ float silu_(float x) { return x * rcp_(1.f + __expf(-x)); }
; template <int EPI>
; __device__ __forceinline__ void gemm_phase(const Params& p, const u16* __restrict__ A, const u16* __restrict__ Bt, int K, int nN,
;                            u16* __restrict__ Cout, int ldc) {
;     ...
;     if (EPI == EPI_GU) {
; #pragma unroll
;       for (int m = 0; m < 8; ++m) {
; #pragma unroll
;         for (int j = 0; j < 4; ++j) {
;           const float rs = rsl[wr * 128 + m * 16 + fqe * 4 + j];
;           u16* d = stg + (wr * 128 + m * 16 + fqe * 4 + j) * 128 + (fre & 7);
; #pragma unroll
;           for (int n2 = 0; n2 < 2; ++n2) {
;             const float g = acc[m][2 * n2][j] * rs, u = acc[m][2 * n2 + 1][j] * rs;
;             const int chunk = (wc * 4 + n2 * 2 + (fre >> 3)) ^ fqe;
;             d[chunk * 8] = f2bf(silu_(g) * u);
;           }
;         }
;         __builtin_amdgcn_sched_barrier(0);
;       }
	v_pk_mul_f32 v[206:207], v[88:89], v[136:137]
	v_pk_mul_f32 v[208:209], v[90:91], v[138:139]
	v_pk_mul_f32 v[210:211], v[80:81], v[136:137]
	v_pk_mul_f32 v[212:213], v[82:83], v[138:139]
	v_pk_add_f32 v[214:215], v[214:215], v[230:231]
	v_pk_add_f32 v[216:217], v[216:217], v[230:231]
	v_pk_add_f32 v[218:219], v[218:219], v[230:231]
	v_pk_add_f32 v[220:221], v[220:221], v[230:231]
	v_rcp_f32_e32 v214, v214
	v_rcp_f32_e32 v215, v215
	v_rcp_f32_e32 v216, v216
	v_rcp_f32_e32 v217, v217
	v_rcp_f32_e32 v218, v218
	v_rcp_f32_e32 v219, v219
	v_rcp_f32_e32 v220, v220
	v_rcp_f32_e32 v221, v221
	v_pk_mul_f32 v[162:163], v[162:163], v[214:215]
	v_pk_mul_f32 v[164:165], v[164:165], v[216:217]
	v_pk_mul_f32 v[166:167], v[166:167], v[218:219]
	v_pk_mul_f32 v[168:169], v[168:169], v[220:221]
	v_pk_mul_f32 v[206:207], v[206:207], v[162:163]
	v_pk_mul_f32 v[208:209], v[208:209], v[164:165]
	v_pk_mul_f32 v[210:211], v[210:211], v[166:167]
	v_pk_mul_f32 v[212:213], v[212:213], v[168:169]
	v_cvt_pk_bf16_f32 v206, v206, v207
	v_cvt_pk_bf16_f32 v208, v208, v209
	v_cvt_pk_bf16_f32 v210, v210, v211
	v_cvt_pk_bf16_f32 v212, v212, v213
	ds_write_b16 v160, v206 offset:8192
	ds_write_b16_d16_hi v160, v206 offset:8448
	ds_write_b16 v160, v208 offset:8704
	ds_write_b16_d16_hi v160, v208 offset:8960
	ds_write_b16 v161, v210 offset:8192
	ds_write_b16_d16_hi v161, v210 offset:8448
	ds_write_b16 v161, v212 offset:8704
	ds_write_b16_d16_hi v161, v212 offset:8960
	v_pk_mul_f32 v[162:163], v[76:77], v[140:141]
	v_pk_mul_f32 v[164:165], v[78:79], v[142:143]
	v_pk_mul_f32 v[166:167], v[68:69], v[140:141]
	v_pk_mul_f32 v[168:169], v[70:71], v[142:143]
	v_pk_mul_f32 v[214:215], v[162:163], v[228:229]
	v_pk_mul_f32 v[216:217], v[164:165], v[228:229]
	v_pk_mul_f32 v[218:219], v[166:167], v[228:229]
	v_pk_mul_f32 v[220:221], v[168:169], v[228:229]
	v_exp_f32_e32 v214, v214
	v_exp_f32_e32 v215, v215
	v_exp_f32_e32 v216, v216
	v_exp_f32_e32 v217, v217
	v_exp_f32_e32 v218, v218
	v_exp_f32_e32 v219, v219
	v_exp_f32_e32 v220, v220
	v_exp_f32_e32 v221, v221
	v_pk_mul_f32 v[206:207], v[72:73], v[140:141]
	v_pk_mul_f32 v[208:209], v[74:75], v[142:143]
	v_pk_mul_f32 v[210:211], v[64:65], v[140:141]
	v_pk_mul_f32 v[212:213], v[66:67], v[142:143]
	v_pk_add_f32 v[214:215], v[214:215], v[230:231]
	v_pk_add_f32 v[216:217], v[216:217], v[230:231]
	v_pk_add_f32 v[218:219], v[218:219], v[230:231]
	v_pk_add_f32 v[220:221], v[220:221], v[230:231]
	v_rcp_f32_e32 v214, v214
	v_rcp_f32_e32 v215, v215
	v_rcp_f32_e32 v216, v216
	v_rcp_f32_e32 v217, v217
	v_rcp_f32_e32 v218, v218
	v_rcp_f32_e32 v219, v219
	v_rcp_f32_e32 v220, v220
	v_rcp_f32_e32 v221, v221
	v_pk_mul_f32 v[162:163], v[162:163], v[214:215]
	v_pk_mul_f32 v[164:165], v[164:165], v[216:217]
	v_pk_mul_f32 v[166:167], v[166:167], v[218:219]
	v_pk_mul_f32 v[168:169], v[168:169], v[220:221]
	v_pk_mul_f32 v[206:207], v[206:207], v[162:163]
	v_pk_mul_f32 v[208:209], v[208:209], v[164:165]
	v_pk_mul_f32 v[210:211], v[210:211], v[166:167]
	v_pk_mul_f32 v[212:213], v[212:213], v[168:169]
	v_cvt_pk_bf16_f32 v206, v206, v207
	v_cvt_pk_bf16_f32 v208, v208, v209
	v_cvt_pk_bf16_f32 v210, v210, v211
	v_cvt_pk_bf16_f32 v212, v212, v213
	ds_write_b16 v160, v206 offset:12288
	ds_write_b16_d16_hi v160, v206 offset:12544
	ds_write_b16 v160, v208 offset:12800
	ds_write_b16_d16_hi v160, v208 offset:13056
	ds_write_b16 v161, v210 offset:12288
	ds_write_b16_d16_hi v161, v210 offset:12544
	ds_write_b16 v161, v212 offset:12800
	ds_write_b16_d16_hi v161, v212 offset:13056
	v_pk_mul_f32 v[162:163], v[60:61], v[144:145]
	v_pk_mul_f32 v[164:165], v[62:63], v[146:147]
	v_pk_mul_f32 v[166:167], v[52:53], v[144:145]
	v_pk_mul_f32 v[168:169], v[54:55], v[146:147]
	v_pk_mul_f32 v[214:215], v[162:163], v[228:229]
	v_pk_mul_f32 v[216:217], v[164:165], v[228:229]
	v_pk_mul_f32 v[218:219], v[166:167], v[228:229]
	v_pk_mul_f32 v[220:221], v[168:169], v[228:229]
	v_exp_f32_e32 v214, v214
	v_exp_f32_e32 v215, v215
	v_exp_f32_e32 v216, v216
	v_exp_f32_e32 v217, v217
	v_exp_f32_e32 v218, v218
	v_exp_f32_e32 v219, v219
	v_exp_f32_e32 v220, v220
	v_exp_f32_e32 v221, v221
	v_pk_mul_f32 v[206:207], v[56:57], v[144:145]
	v_pk_mul_f32 v[208:209], v[58:59], v[146:147]
	v_pk_mul_f32 v[210:211], v[48:49], v[144:145]
	v_pk_mul_f32 v[212:213], v[50:51], v[146:147]
	v_pk_add_f32 v[214:215], v[214:215], v[230:231]
	v_pk_add_f32 v[216:217], v[216:217], v[230:231]
	v_pk_add_f32 v[218:219], v[218:219], v[230:231]
	v_pk_add_f32 v[220:221], v[220:221], v[230:231]
	v_rcp_f32_e32 v214, v214
	v_rcp_f32_e32 v215, v215
	v_rcp_f32_e32 v216, v216
	v_rcp_f32_e32 v217, v217
	v_rcp_f32_e32 v218, v218
	v_rcp_f32_e32 v219, v219
	v_rcp_f32_e32 v220, v220
	v_rcp_f32_e32 v221, v221
	v_pk_mul_f32 v[162:163], v[162:163], v[214:215]
	v_pk_mul_f32 v[164:165], v[164:165], v[216:217]
	v_pk_mul_f32 v[166:167], v[166:167], v[218:219]
	v_pk_mul_f32 v[168:169], v[168:169], v[220:221]
	v_pk_mul_f32 v[206:207], v[206:207], v[162:163]
	v_pk_mul_f32 v[208:209], v[208:209], v[164:165]
	v_pk_mul_f32 v[210:211], v[210:211], v[166:167]
	v_pk_mul_f32 v[212:213], v[212:213], v[168:169]
	v_cvt_pk_bf16_f32 v206, v206, v207
	v_cvt_pk_bf16_f32 v208, v208, v209
	v_cvt_pk_bf16_f32 v210, v210, v211
	v_cvt_pk_bf16_f32 v212, v212, v213
	ds_write_b16 v160, v206 offset:16384
	ds_write_b16_d16_hi v160, v206 offset:16640
	ds_write_b16 v160, v208 offset:16896
	ds_write_b16_d16_hi v160, v208 offset:17152
	ds_write_b16 v161, v210 offset:16384
	ds_write_b16_d16_hi v161, v210 offset:16640
	ds_write_b16 v161, v212 offset:16896
	ds_write_b16_d16_hi v161, v212 offset:17152
	v_pk_mul_f32 v[162:163], v[44:45], v[148:149]
	v_pk_mul_f32 v[164:165], v[46:47], v[150:151]
; __device__ __forceinline__ float silu_(float x) { return x * rcp_(1.f + __expf(-x)); }
; template <int EPI>
; __device__ __forceinline__ void gemm_phase(const Params& p, const u16* __restrict__ A, const u16* __restrict__ Bt, int K, int nN,
;                            u16* __restrict__ Cout, int ldc) {
;     ...
;     if (EPI == EPI_GU) {
; #pragma unroll
;       for (int m = 0; m < 8; ++m) {
; #pragma unroll
;         for (int j = 0; j < 4; ++j) {
;           const float rs = rsl[wr * 128 + m * 16 + fqe * 4 + j];
;           u16* d = stg + (wr * 128 + m * 16 + fqe * 4 + j) * 128 + (fre & 7);
; #pragma unroll
;           for (int n2 = 0; n2 < 2; ++n2) {
;             const float g = acc[m][2 * n2][j] * rs, u = acc[m][2 * n2 + 1][j] * rs;
;             const int chunk = (wc * 4 + n2 * 2 + (fre >> 3)) ^ fqe;
;             d[chunk * 8] = f2bf(silu_(g) * u);
;           }
;         }
;         __builtin_amdgcn_sched_barrier(0);
;       }
;       __syncthreads();
; #pragma unroll
;       for (int it = 0; it < 8; ++it) {
;         const int id = it * 512 + tide, r = id >> 4, ck = id & 15;
	v_pk_mul_f32 v[166:167], v[36:37], v[148:149]
	v_pk_mul_f32 v[168:169], v[38:39], v[150:151]
	v_pk_mul_f32 v[214:215], v[162:163], v[228:229]
	v_pk_mul_f32 v[216:217], v[164:165], v[228:229]
	v_pk_mul_f32 v[218:219], v[166:167], v[228:229]
	v_pk_mul_f32 v[220:221], v[168:169], v[228:229]
	v_exp_f32_e32 v214, v214
	v_exp_f32_e32 v215, v215
	v_exp_f32_e32 v216, v216
	v_exp_f32_e32 v217, v217
	v_exp_f32_e32 v218, v218
	v_exp_f32_e32 v219, v219
	v_exp_f32_e32 v220, v220
	v_exp_f32_e32 v221, v221
	v_pk_mul_f32 v[206:207], v[40:41], v[148:149]
	v_pk_mul_f32 v[208:209], v[42:43], v[150:151]
	v_pk_mul_f32 v[210:211], v[32:33], v[148:149]
	v_pk_mul_f32 v[212:213], v[34:35], v[150:151]
	v_pk_add_f32 v[214:215], v[214:215], v[230:231]
	v_pk_add_f32 v[216:217], v[216:217], v[230:231]
	v_pk_add_f32 v[218:219], v[218:219], v[230:231]
	v_pk_add_f32 v[220:221], v[220:221], v[230:231]
	v_rcp_f32_e32 v214, v214
	v_rcp_f32_e32 v215, v215
	v_rcp_f32_e32 v216, v216
	v_rcp_f32_e32 v217, v217
	v_rcp_f32_e32 v218, v218
	v_rcp_f32_e32 v219, v219
	v_rcp_f32_e32 v220, v220
	v_rcp_f32_e32 v221, v221
	v_pk_mul_f32 v[162:163], v[162:163], v[214:215]
	v_pk_mul_f32 v[164:165], v[164:165], v[216:217]
	v_pk_mul_f32 v[166:167], v[166:167], v[218:219]
	v_pk_mul_f32 v[168:169], v[168:169], v[220:221]
	v_pk_mul_f32 v[206:207], v[206:207], v[162:163]
	v_pk_mul_f32 v[208:209], v[208:209], v[164:165]
	v_pk_mul_f32 v[210:211], v[210:211], v[166:167]
	v_pk_mul_f32 v[212:213], v[212:213], v[168:169]
	v_cvt_pk_bf16_f32 v206, v206, v207
	v_cvt_pk_bf16_f32 v208, v208, v209
	v_cvt_pk_bf16_f32 v210, v210, v211
	v_cvt_pk_bf16_f32 v212, v212, v213
	ds_write_b16 v160, v206 offset:20480
	ds_write_b16_d16_hi v160, v206 offset:20736
	ds_write_b16 v160, v208 offset:20992
	ds_write_b16_d16_hi v160, v208 offset:21248
	ds_write_b16 v161, v210 offset:20480
	ds_write_b16_d16_hi v161, v210 offset:20736
	ds_write_b16 v161, v212 offset:20992
	ds_write_b16_d16_hi v161, v212 offset:21248
	v_pk_mul_f32 v[162:163], v[28:29], v[152:153]
	v_pk_mul_f32 v[164:165], v[30:31], v[154:155]
	v_pk_mul_f32 v[166:167], v[20:21], v[152:153]
	v_pk_mul_f32 v[168:169], v[22:23], v[154:155]
	v_pk_mul_f32 v[214:215], v[162:163], v[228:229]
	v_pk_mul_f32 v[216:217], v[164:165], v[228:229]
	v_pk_mul_f32 v[218:219], v[166:167], v[228:229]
	v_pk_mul_f32 v[220:221], v[168:169], v[228:229]
	v_exp_f32_e32 v214, v214
	v_exp_f32_e32 v215, v215
	v_exp_f32_e32 v216, v216
	v_exp_f32_e32 v217, v217
	v_exp_f32_e32 v218, v218
	v_exp_f32_e32 v219, v219
	v_exp_f32_e32 v220, v220
	v_exp_f32_e32 v221, v221
	v_pk_mul_f32 v[206:207], v[24:25], v[152:153]
	v_pk_mul_f32 v[208:209], v[26:27], v[154:155]
	v_pk_mul_f32 v[210:211], v[16:17], v[152:153]
	v_pk_mul_f32 v[212:213], v[18:19], v[154:155]
	v_pk_add_f32 v[214:215], v[214:215], v[230:231]
	v_pk_add_f32 v[216:217], v[216:217], v[230:231]
	v_pk_add_f32 v[218:219], v[218:219], v[230:231]
	v_pk_add_f32 v[220:221], v[220:221], v[230:231]
	v_rcp_f32_e32 v214, v214
	v_rcp_f32_e32 v215, v215
	v_rcp_f32_e32 v216, v216
	v_rcp_f32_e32 v217, v217
	v_rcp_f32_e32 v218, v218
	v_rcp_f32_e32 v219, v219
	v_rcp_f32_e32 v220, v220
	v_rcp_f32_e32 v221, v221
	v_pk_mul_f32 v[162:163], v[162:163], v[214:215]
	v_pk_mul_f32 v[164:165], v[164:165], v[216:217]
	v_pk_mul_f32 v[166:167], v[166:167], v[218:219]
	v_pk_mul_f32 v[168:169], v[168:169], v[220:221]
	v_pk_mul_f32 v[206:207], v[206:207], v[162:163]
	v_pk_mul_f32 v[208:209], v[208:209], v[164:165]
	v_pk_mul_f32 v[210:211], v[210:211], v[166:167]
	v_pk_mul_f32 v[212:213], v[212:213], v[168:169]
	v_cvt_pk_bf16_f32 v206, v206, v207
	v_cvt_pk_bf16_f32 v208, v208, v209
	v_cvt_pk_bf16_f32 v210, v210, v211
	v_cvt_pk_bf16_f32 v212, v212, v213
	ds_write_b16 v160, v206 offset:24576
	ds_write_b16_d16_hi v160, v206 offset:24832
	ds_write_b16 v160, v208 offset:25088
	ds_write_b16_d16_hi v160, v208 offset:25344
	ds_write_b16 v161, v210 offset:24576
	ds_write_b16_d16_hi v161, v210 offset:24832
	ds_write_b16 v161, v212 offset:25088
	ds_write_b16_d16_hi v161, v212 offset:25344
	v_pk_mul_f32 v[162:163], v[12:13], v[156:157]
	v_pk_mul_f32 v[164:165], v[14:15], v[158:159]
	v_pk_mul_f32 v[166:167], v[4:5], v[156:157]
	v_pk_mul_f32 v[168:169], v[6:7], v[158:159]
	v_pk_mul_f32 v[214:215], v[162:163], v[228:229]
	v_pk_mul_f32 v[216:217], v[164:165], v[228:229]
	v_pk_mul_f32 v[218:219], v[166:167], v[228:229]
	v_pk_mul_f32 v[220:221], v[168:169], v[228:229]
	v_exp_f32_e32 v214, v214
	v_exp_f32_e32 v215, v215
	v_exp_f32_e32 v216, v216
	v_exp_f32_e32 v217, v217
	v_exp_f32_e32 v218, v218
	v_exp_f32_e32 v219, v219
	v_exp_f32_e32 v220, v220
	v_exp_f32_e32 v221, v221
	v_pk_mul_f32 v[206:207], v[8:9], v[156:157]
	v_pk_mul_f32 v[208:209], v[10:11], v[158:159]
	v_pk_mul_f32 v[210:211], v[0:1], v[156:157]
	v_pk_mul_f32 v[212:213], v[2:3], v[158:159]
	v_pk_add_f32 v[214:215], v[214:215], v[230:231]
	v_pk_add_f32 v[216:217], v[216:217], v[230:231]
	v_pk_add_f32 v[218:219], v[218:219], v[230:231]
	v_pk_add_f32 v[220:221], v[220:221], v[230:231]
	v_rcp_f32_e32 v214, v214
	v_rcp_f32_e32 v215, v215
	v_rcp_f32_e32 v216, v216
	v_rcp_f32_e32 v217, v217
	v_rcp_f32_e32 v218, v218
	v_rcp_f32_e32 v219, v219
	v_rcp_f32_e32 v220, v220
	v_rcp_f32_e32 v221, v221
	v_pk_mul_f32 v[162:163], v[162:163], v[214:215]
	v_pk_mul_f32 v[164:165], v[164:165], v[216:217]
	v_pk_mul_f32 v[166:167], v[166:167], v[218:219]
	v_pk_mul_f32 v[168:169], v[168:169], v[220:221]
	v_pk_mul_f32 v[206:207], v[206:207], v[162:163]
	v_pk_mul_f32 v[208:209], v[208:209], v[164:165]
	v_pk_mul_f32 v[210:211], v[210:211], v[166:167]
	v_pk_mul_f32 v[212:213], v[212:213], v[168:169]
	v_cvt_pk_bf16_f32 v206, v206, v207
	v_cvt_pk_bf16_f32 v208, v208, v209
	v_cvt_pk_bf16_f32 v210, v210, v211
	v_cvt_pk_bf16_f32 v212, v212, v213
	ds_write_b16 v160, v206 offset:28672
	ds_write_b16_d16_hi v160, v206 offset:28928
	ds_write_b16 v160, v208 offset:29184
	ds_write_b16_d16_hi v160, v208 offset:29440
	ds_write_b16 v161, v210 offset:28672
	ds_write_b16_d16_hi v161, v210 offset:28928
	ds_write_b16 v161, v212 offset:29184
	ds_write_b16_d16_hi v161, v212 offset:29440
	v_mov_b32_e32 v128, v173
	v_and_b32_e32 v0, 15, v128
	v_lshrrev_b32_e32 v1, 6, v128
	v_bitop3_b32 v1, v1, v0, 3 bitop3:0x6c
	s_lshl_b32 s2, s39, 7
	v_lshl_or_b32 v8, v1, 4, v188
	v_lshl_or_b32 v0, v0, 3, s2
	v_mov_b32_e32 v1, v172
	v_ashrrev_i32_e32 v6, 4, v128
	v_lshl_add_u64 v[4:5], v[0:1], 1, s[4:5]
	v_lshl_add_u32 v0, v6, 8, v8
	s_waitcnt lgkmcnt(0)
	s_barrier
; template <int EPI>
; __device__ __forceinline__ void gemm_phase(const Params& p, const u16* __restrict__ A, const u16* __restrict__ Bt, int K, int nN,
;                            u16* __restrict__ Cout, int ldc) {
;     ...
; #pragma unroll
;       for (int it = 0; it < 8; ++it) {
;         const int id = it * 512 + tide, r = id >> 4, ck = id & 15;
;         const uint4 v = *(const uint4*)(stg + r * 128 + ((ck ^ ((r >> 2) & 3)) * 8));
;         { typedef __attribute__((ext_vector_type(4))) unsigned u32x4_; const u32x4_ t_ = {v.x, v.y, v.z, v.w};
;           __builtin_nontemporal_store(t_, (u32x4_*)(Cout + (unsigned)(brow + r) * (unsigned)ldc + (unsigned)((bcol >> 1) + ck * 8))); }
;       }
;       asm volatile("s_waitcnt lgkmcnt(0)" ::: "memory"); __builtin_amdgcn_s_barrier();
	ds_read_b128 v[16:19], v0 offset:0
	ds_read_b128 v[20:23], v0 offset:8192
	ds_read_b128 v[24:27], v0 offset:16384
	ds_read_b128 v[28:31], v0 offset:24576
	ds_read_b128 v[32:35], v0 offset:32768
	ds_read_b128 v[36:39], v0 offset:40960
	ds_read_b128 v[40:43], v0 offset:49152
	ds_read_b128 v[44:47], v0 offset:57344
	v_add_u32_e32 v6, s12, v6
	v_mul_lo_u32 v6, v6, s58
	v_mov_b32_e32 v7, v172
	v_lshl_add_u64 v[48:49], v[6:7], 1, v[4:5]
	s_mov_b64 s[2:3], 0x2c000
	s_mov_b64 s[26:27], -1
	s_and_b64 vcc, exec, s[14:15]
	v_lshl_add_u64 v[50:51], v[48:49], 0, s[2:3]
	v_lshl_add_u64 v[52:53], v[50:51], 0, s[2:3]
	v_lshl_add_u64 v[54:55], v[52:53], 0, s[2:3]
	v_lshl_add_u64 v[56:57], v[54:55], 0, s[2:3]
	v_lshl_add_u64 v[58:59], v[56:57], 0, s[2:3]
	v_lshl_add_u64 v[60:61], v[58:59], 0, s[2:3]
	v_lshl_add_u64 v[62:63], v[60:61], 0, s[2:3]
	s_waitcnt lgkmcnt(7)
	global_store_dwordx4 v[48:49], v[16:19], off sc0 sc1 nt
	s_waitcnt lgkmcnt(6)
	global_store_dwordx4 v[50:51], v[20:23], off sc0 sc1 nt
	s_waitcnt lgkmcnt(5)
	global_store_dwordx4 v[52:53], v[24:27], off sc0 sc1 nt
	s_waitcnt lgkmcnt(4)
	global_store_dwordx4 v[54:55], v[28:31], off sc0 sc1 nt
	s_waitcnt lgkmcnt(3)
	global_store_dwordx4 v[56:57], v[32:35], off sc0 sc1 nt
	s_waitcnt lgkmcnt(2)
	global_store_dwordx4 v[58:59], v[36:39], off sc0 sc1 nt
	s_waitcnt lgkmcnt(1)
	global_store_dwordx4 v[60:61], v[40:43], off sc0 sc1 nt
	s_waitcnt lgkmcnt(0)
	global_store_dwordx4 v[62:63], v[44:47], off sc0 sc1 nt
	s_waitcnt lgkmcnt(0)
	s_barrier
	s_cbranch_vccnz .LBB0_1153

; __device__ __forceinline__ unsigned xb_add(unsigned* p, unsigned v) { return __hip_atomic_fetch_add(p, v, __ATOMIC_RELAXED, __HIP_MEMORY_SCOPE_AGENT); }
; __device__ __forceinline__ void xcd_barrier(const XcdBarrier& b, unsigned gen) {
;   asm volatile("s_waitcnt vmcnt(0)" ::: "memory");
;   __syncthreads();
;   if (threadIdx.x == 0) {
;     unsigned* bar = b.bar;
;     __builtin_amdgcn_s_waitcnt(0);
;     const unsigned old = xb_add(&bar[XB_XSUB(b.x)], 1u);
;     if (old + 1u == (gen + 1u) * b.nloc) {
;       __builtin_amdgcn_fence(__ATOMIC_RELEASE, "agent");
;       asm volatile("s_waitcnt vmcnt(0)" ::: "memory");
;       const unsigned og = xb_add(&bar[XB_TOP], 1u);
;       const unsigned tg = gen;
;       if (og + 1u == (tg + 1u) * b.nx) xb_add(&bar[XB_TOPGEN], 1u);
.LBB0_1173:
	s_andn2_saveexec_b64 s[2:3], s[2:3]
	s_cbranch_execz .LBB0_709
	s_mov_b64 s[2:3], exec
	s_add_i32 s4, s12, -1
	s_mul_i32 s5, s4, 43
	s_lshr_b32 s5, s5, 9
	s_mul_i32 s5, s5, 12
	s_sub_i32 s4, s4, s5
	s_sub_i32 s4, s4, 4
	s_cmp_gt_u32 s4, 2
	s_cbranch_scc1 .Lbar_nowb
	buffer_wbl2 sc1
.Lbar_nowb:
	s_waitcnt vmcnt(0)
	v_mbcnt_lo_u32_b32 v0, s2, 0
	v_mbcnt_hi_u32_b32 v0, s3, v0
	v_cmp_eq_u32_e32 vcc, 0, v0
	s_and_saveexec_b64 s[4:5], vcc
	s_cbranch_execz .LBB0_1176
	s_bcnt1_i32_b64 s2, s[2:3]
	v_mov_b32_e32 v1, s2
	v_readlane_b32 s2, v249, 11
	v_readlane_b32 s3, v249, 12
	s_nop 4
	global_atomic_add v1, v172, v1, s[2:3] sc0
